# attention: skip fully masked wave-tiles, single PV wait, cross-half max only on rescale path
# speedup vs baseline: 1.0306x; 1.0116x over previous
; #define LAS __attribute__((address_space(3)))
; __global__ void __launch_bounds__(512, 2) trunk_fwd(Args args) {
;     extern __shared__ __attribute__((aligned(16))) unsigned char lds_raw[];
;     LAS unsigned char* lds = (LAS unsigned char*)lds_raw;
;     volatile LAS unsigned* MISC = (volatile LAS unsigned*)(lds + MISC_OFF);
;     for (int u = threadIdx.x; u < 32; u += 512) MISC[u] = (u == 16) ? blockIdx.x : 0u;
;     __syncthreads();
;     XcdBarrier bar = xcd_barrier_post((unsigned*)(args.ws + WS_CTL) + 1024, MISC + 8);
_Z9trunk_fwd4Args:
	s_mov_b32 s100, 0
	v_writelane_b32 v255, s100, 40
	s_mov_b64 s[94:95], s[0:1]
	s_load_dwordx2 s[0:1], s[0:1], 0xc0
	v_and_b32_e32 v163, 0x3ff, v0
	v_cmp_gt_u32_e32 vcc, 32, v163
	s_and_saveexec_b64 s[4:5], vcc
	s_cbranch_execz .LBB0_2
	v_mov_b32_e32 v1, s2
	v_cmp_eq_u32_e32 vcc, 16, v163
	v_lshl_add_u32 v2, v163, 2, 0
	v_add_u32_e32 v2, 0x20140, v2
	v_cndmask_b32_e32 v1, 0, v1, vcc
	ds_write_b32 v2, v1

; __device__ __forceinline__ unsigned xb_ld(unsigned* p)              { return __hip_atomic_load(p, __ATOMIC_RELAXED, __HIP_MEMORY_SCOPE_AGENT); }
; __device__ __forceinline__ unsigned xb_add(unsigned* p, unsigned v) { return __hip_atomic_fetch_add(p, v, __ATOMIC_RELAXED, __HIP_MEMORY_SCOPE_AGENT); }
; #define XB_SPIN(cond, bar) do { unsigned _sp = 0; while (cond) { __builtin_amdgcn_s_sleep(1); \
;     if ((++_sp & 255u) == 0u) { if (xb_ld(&(bar)[XB_TMO])) break; if (_sp > XB_SPIN_CAP) { atomicAdd(&(bar)[XB_TMO], 1u); break; } } } } while (0)
; __device__ __forceinline__ void xcd_local_barrier(const XcdBarrier& b, unsigned nloc) {
;     asm volatile("s_waitcnt vmcnt(0)" ::: "memory");
;     __syncthreads();
;     if (threadIdx.x == 0) {
;         unsigned* bar = b.bar;
;         __builtin_amdgcn_s_waitcnt(0);
;         const unsigned old = xb_add(&bar[XB_LSUB(b.x)], 1u);
;         const unsigned gen = old / nloc;
;         if (old + 1u == (gen + 1u) * nloc) xb_add(&bar[XB_LGEN(b.x)], 1u);
;         else XB_SPIN(xb_ld(&bar[XB_LGEN(b.x)]) == gen, bar);
;         __builtin_amdgcn_fence(__ATOMIC_ACQUIRE, "agent");
;         asm volatile("s_waitcnt vmcnt(0)" ::: "memory");
;     }
;     __syncthreads();
; }
.LBB0_507:
	v_readlane_b32 s4, v254, 60
	v_mov_b32 v0, s4
	ds_read_b32 v0, v0
	s_waitcnt lgkmcnt(0)
	s_nop 0
	v_readfirstlane_b32 s4, v0
	s_cmp_eq_u32 s4, 0
	s_cbranch_scc1 .LBB0_521
	s_waitcnt vmcnt(0)
	s_waitcnt lgkmcnt(0)
	s_barrier
	s_and_saveexec_b64 s[18:19], s[92:93]
	v_readlane_b32 s6, v255, 17
	v_readlane_b32 s7, v255, 18
	s_cbranch_execz .LBB0_527
	v_readlane_b32 s100, v255, 40
	v_readlane_b32 s4, v254, 6
	v_readlane_b32 s5, v254, 7
	s_mov_b32 s101, 0
	s_add_u32 s100, s100, 32
	s_nop 1
	v_writelane_b32 v255, s100, 40
	global_atomic_add v1, v218, s[4:5]
	buffer_inv sc1
.Llb_spin_0:
	global_load_dword v2, v1, s[4:5] sc1
	s_waitcnt vmcnt(0)
	v_cmp_le_u32_e32 vcc, s100, v2
	s_cbranch_vccnz .Llb_done_0
	s_sleep 1
	s_add_u32 s101, s101, 1
	s_cmp_lt_u32 s101, 0x4000
	s_cbranch_scc1 .Llb_spin_0

; __device__ __forceinline__ unsigned xb_ld(unsigned* p)              { return __hip_atomic_load(p, __ATOMIC_RELAXED, __HIP_MEMORY_SCOPE_AGENT); }
; __device__ __forceinline__ unsigned xb_add(unsigned* p, unsigned v) { return __hip_atomic_fetch_add(p, v, __ATOMIC_RELAXED, __HIP_MEMORY_SCOPE_AGENT); }
; #define XB_SPIN(cond, bar) do { unsigned _sp = 0; while (cond) { __builtin_amdgcn_s_sleep(1); \
;     if ((++_sp & 255u) == 0u) { if (xb_ld(&(bar)[XB_TMO])) break; if (_sp > XB_SPIN_CAP) { atomicAdd(&(bar)[XB_TMO], 1u); break; } } } } while (0)
; __device__ __forceinline__ void xcd_local_barrier(const XcdBarrier& b, unsigned nloc) {
;     asm volatile("s_waitcnt vmcnt(0)" ::: "memory");
;     __syncthreads();
;     if (threadIdx.x == 0) {
;         unsigned* bar = b.bar;
;         __builtin_amdgcn_s_waitcnt(0);
;         const unsigned old = xb_add(&bar[XB_LSUB(b.x)], 1u);
;         const unsigned gen = old / nloc;
;         if (old + 1u == (gen + 1u) * nloc) xb_add(&bar[XB_LGEN(b.x)], 1u);
;         else XB_SPIN(xb_ld(&bar[XB_LGEN(b.x)]) == gen, bar);
;         __builtin_amdgcn_fence(__ATOMIC_ACQUIRE, "agent");
;         asm volatile("s_waitcnt vmcnt(0)" ::: "memory");
;     }
;     __syncthreads();
; }
.LBB0_731:
	v_readlane_b32 s0, v254, 60
	v_mov_b32 v0, s0
	ds_read_b32 v0, v0
	s_waitcnt lgkmcnt(0)
	s_nop 0
	v_readfirstlane_b32 s0, v0
	s_cmp_eq_u32 s0, 0
	s_cbranch_scc1 .LBB0_745
	s_waitcnt vmcnt(0)
	s_waitcnt vmcnt(0) lgkmcnt(0)
	s_barrier
	s_and_saveexec_b64 s[0:1], s[92:93]
	v_readlane_b32 s6, v255, 17
	v_readlane_b32 s7, v255, 18
	s_cbranch_execz .LBB0_751
	v_readlane_b32 s100, v255, 40
	v_readlane_b32 s4, v254, 6
	v_readlane_b32 s5, v254, 7
	s_mov_b32 s101, 0
	s_add_u32 s100, s100, 32
	s_nop 1
	v_writelane_b32 v255, s100, 40
	global_atomic_add v1, v218, s[4:5]
	buffer_inv sc1

; #define SBAR() __builtin_amdgcn_sched_barrier(0)
; #define WAIT_BAR(N) asm volatile("s_waitcnt vmcnt(" #N ") lgkmcnt(0)\n\ts_barrier" ::: "memory")
; #define DMA_TILE(t, ks, vs) do { glds16(ksrc + (long)(t) * KVBLK * KNP, (unsigned)__builtin_amdgcn_readfirstlane(kdst + (ks) * KSLOT)); \
;         glds16(k2src + (long)(t) * KVBLK * KPP, (unsigned)__builtin_amdgcn_readfirstlane(k2dst + (ks) * KSLOT)); \
;         glds16(vsrc + (long)(t) * KVBLK * VP, (unsigned)__builtin_amdgcn_readfirstlane(vdst + (vs) * VSLOT)); } while (0)
; #define K_LOAD(ks) do { const LAS char* kp_ = kp0 + (ks) * KSLOT; \
;         _Pragma("unroll") for (int i_ = 0; i_ < 6; ++i_) { kf[2 * i_] = *(const LAS bf16x8*)(kp_ + i_ * 2048); kf[2 * i_ + 1] = *(const LAS bf16x8*)(kp_ + i_ * 2048 + 512); } SBAR(); } while (0)
; #define V_LOAD(vs) do { const LAS char* vp_ = vp0 + (vs) * VSLOT; \
;         _Pragma("unroll") for (int i_ = 0; i_ < 8; ++i_) { vlo[i_] = vtr(vp_ + ((i_ >> 2) * 4096 + (i_ & 3) * 1024)); vhi[i_] = vtr(vp_ + ((i_ >> 2) * 4096 + (i_ & 3) * 1024 + 512)); } SBAR(); } while (0)
; __device__ __forceinline__ void attn_unit(int b, int h, int qb, const bf16* Q, const bf16* __restrict__ Kn, const bf16* __restrict__ Kpe, const bf16* __restrict__ V, bf16* O, float* ASS, LAS char* shm) {
;     ...
;         for (int t = 0; t < NT; ++t) {
;             if (t + 1 < NT) { WAIT_BAR(3); } else { WAIT_BAR(0); }
;             if (t > 0) V_LOAD((vs + 3) & 3);
;             if (t + 2 < NT) DMA_TILE(t + 2, (ks == 0) ? 2 : ks - 1, (vs + 2) & 3);
;             SBAR();
;             if (t > 0) SOFTMAX();
;             K_LOAD(ks);
;             if (t > 0) PV_MMA();
;             QK_MMA(t);
.Lat_u1x_bar:
	s_barrier
	s_lshr_b32 s4, s69, 1
	s_sub_u32 s4, s52, s4
	s_cmp_gt_i32 s4, s87
	s_cbranch_scc1 .Lat_u1x_noqk
	s_mul_i32 s53, s48, 0x3000
	v_add_u32_e32 v158, s53, v146
	ds_read_b128 v[196:199], v158
	ds_read_b128 v[200:203], v158 offset:512
	ds_read_b128 v[204:207], v158 offset:2048
	ds_read_b128 v[208:211], v158 offset:2560
	ds_read_b128 v[212:215], v158 offset:4096
	ds_read_b128 v[230:233], v158 offset:4608
	ds_read_b128 v[234:237], v158 offset:6144
	ds_read_b128 v[164:167], v158 offset:6656
	ds_read_b128 v[168:171], v158 offset:8192
	ds_read_b128 v[172:175], v158 offset:8704
	ds_read_b128 v[148:151], v158 offset:10240
	ds_read_b128 v[152:155], v158 offset:10752
	s_lshl_b32 s4, s50, 13
	s_add_i32 s4, s4, 0x6000
	s_and_b32 s4, s4, 0x6000
	v_add_u32_e32 v159, s4, v144
	v_mov_b32_e32 v156, 0
	v_mov_b32_e32 v157, 0
	s_waitcnt lgkmcnt(11)
	v_mfma_f32_32x32x16_bf16 v[238:253], v[196:199], v[100:103], v[104:119]
	ds_read_b64_tr_b16 v[196:197], v159 offset:36864
	ds_read_b64_tr_b16 v[198:199], v159 offset:37376
	v_exp_f32_e32 v64, v64
	v_exp_f32_e32 v65, v65
	v_add_f32_e32 v156, v156, v64
	v_add_f32_e32 v156, v156, v65
	v_cvt_pk_bf16_f32 v64, v64, v65
	s_waitcnt lgkmcnt(12)
	v_mfma_f32_32x32x16_bf16 v[180:195], v[200:203], v[100:103], v[104:119]
	ds_read_b64_tr_b16 v[200:201], v159 offset:37888
	ds_read_b64_tr_b16 v[202:203], v159 offset:38400
	v_exp_f32_e32 v66, v66
	v_exp_f32_e32 v67, v67
	v_add_f32_e32 v157, v157, v66
	v_add_f32_e32 v157, v157, v67
	v_cvt_pk_bf16_f32 v65, v66, v67
	s_waitcnt lgkmcnt(13)
	v_mfma_f32_32x32x16_bf16 v[238:253], v[204:207], v[96:99], v[238:253]
	ds_read_b64_tr_b16 v[204:205], v159 offset:38912
	ds_read_b64_tr_b16 v[206:207], v159 offset:39424
	v_exp_f32_e32 v68, v68
	v_exp_f32_e32 v69, v69
	v_add_f32_e32 v156, v156, v68
	v_add_f32_e32 v156, v156, v69
	v_cvt_pk_bf16_f32 v66, v68, v69
	s_waitcnt lgkmcnt(14)
	v_mfma_f32_32x32x16_bf16 v[180:195], v[208:211], v[96:99], v[180:195]
	ds_read_b64_tr_b16 v[208:209], v159 offset:39936
	ds_read_b64_tr_b16 v[210:211], v159 offset:40448
	v_exp_f32_e32 v70, v70
	v_exp_f32_e32 v71, v71
	v_add_f32_e32 v157, v157, v70
	v_add_f32_e32 v157, v157, v71
	v_cvt_pk_bf16_f32 v67, v70, v71
	s_waitcnt lgkmcnt(15)
	v_mfma_f32_32x32x16_bf16 v[238:253], v[212:215], v[92:95], v[238:253]
	ds_read_b64_tr_b16 v[212:213], v159 offset:40960
	ds_read_b64_tr_b16 v[214:215], v159 offset:41472
	v_exp_f32_e32 v72, v72
	v_exp_f32_e32 v73, v73
	v_add_f32_e32 v156, v156, v72
	v_add_f32_e32 v156, v156, v73
	v_cvt_pk_bf16_f32 v68, v72, v73
	s_waitcnt lgkmcnt(15)
	v_mfma_f32_32x32x16_bf16 v[180:195], v[230:233], v[92:95], v[180:195]
	ds_read_b64_tr_b16 v[230:231], v159 offset:41984
	ds_read_b64_tr_b16 v[232:233], v159 offset:42496
	v_exp_f32_e32 v74, v74
	v_exp_f32_e32 v75, v75
	v_add_f32_e32 v157, v157, v74
	v_add_f32_e32 v157, v157, v75
	v_cvt_pk_bf16_f32 v69, v74, v75
	s_waitcnt lgkmcnt(15)
	v_mfma_f32_32x32x16_bf16 v[238:253], v[234:237], v[88:91], v[238:253]
	ds_read_b64_tr_b16 v[234:235], v159 offset:43008
	ds_read_b64_tr_b16 v[236:237], v159 offset:43520
	v_exp_f32_e32 v76, v76
	v_exp_f32_e32 v77, v77
	v_add_f32_e32 v156, v156, v76
	v_add_f32_e32 v156, v156, v77
	v_cvt_pk_bf16_f32 v70, v76, v77
	s_waitcnt lgkmcnt(15)
	v_mfma_f32_32x32x16_bf16 v[180:195], v[164:167], v[88:91], v[180:195]
	ds_read_b64_tr_b16 v[164:165], v159 offset:44032
	ds_read_b64_tr_b16 v[166:167], v159 offset:44544
	v_exp_f32_e32 v78, v78
	v_exp_f32_e32 v79, v79
	v_add_f32_e32 v157, v157, v78
	v_add_f32_e32 v157, v157, v79
	v_cvt_pk_bf16_f32 v71, v78, v79
	s_waitcnt lgkmcnt(15)
	v_mfma_f32_32x32x16_bf16 v[238:253], v[168:171], v[84:87], v[238:253]
	v_exp_f32_e32 v48, v48
	v_exp_f32_e32 v49, v49
	v_add_f32_e32 v156, v156, v48
	v_add_f32_e32 v156, v156, v49
	v_cvt_pk_bf16_f32 v48, v48, v49
	s_waitcnt lgkmcnt(15)
	v_mfma_f32_32x32x16_bf16 v[180:195], v[172:175], v[84:87], v[180:195]
	v_exp_f32_e32 v50, v50
	v_exp_f32_e32 v51, v51
	v_add_f32_e32 v157, v157, v50
	v_add_f32_e32 v157, v157, v51
	v_cvt_pk_bf16_f32 v49, v50, v51
	s_waitcnt lgkmcnt(15)
	v_mfma_f32_32x32x16_bf16 v[238:253], v[148:151], v[80:83], v[238:253]
	v_exp_f32_e32 v52, v52
	v_exp_f32_e32 v53, v53
	v_add_f32_e32 v156, v156, v52
	v_add_f32_e32 v156, v156, v53
	v_cvt_pk_bf16_f32 v50, v52, v53
	s_waitcnt lgkmcnt(15)
	v_mfma_f32_32x32x16_bf16 v[180:195], v[152:155], v[80:83], v[180:195]
	v_exp_f32_e32 v54, v54
	v_exp_f32_e32 v55, v55
	v_add_f32_e32 v157, v157, v54
	v_add_f32_e32 v157, v157, v55
	v_cvt_pk_bf16_f32 v51, v54, v55
	s_nop 1
	s_waitcnt lgkmcnt(0)
	v_mfma_f32_32x32x16_bf16 v[16:31], v[64:67], v[196:199], v[16:31]
	v_exp_f32_e32 v56, v56
	v_exp_f32_e32 v57, v57
	v_add_f32_e32 v156, v156, v56
	v_add_f32_e32 v156, v156, v57
	v_cvt_pk_bf16_f32 v52, v56, v57
	s_nop 1
	v_mfma_f32_32x32x16_bf16 v[32:47], v[64:67], v[212:215], v[32:47]
	s_mul_i32 s53, s48, 0x3000
	s_add_i32 s4, s52, 2
	s_cmp_ge_u32 s4, s86
	s_cbranch_scc1 .Lat_u1x_nodma
	s_add_i32 s4, s53, 0xffffd000
	s_cmp_lg_u32 s48, 0
	s_cselect_b32 s4, s4, 0x6000
	s_add_i32 s5, s4, s97
	s_mov_b32 m0, s5
	s_add_i32 s4, s4, s72
	global_load_lds_dwordx4 v[126:127], off
	s_mov_b32 m0, s4
	s_lshl_b32 s5, s50, 13
	global_load_lds_dwordx4 v[14:15], off
	s_xor_b32 s5, s5, 0x4000
	s_add_i32 s5, s5, s73
	s_mov_b32 m0, s5
	s_nop 0
	global_load_lds_dwordx4 v[124:125], off
; __device__ __forceinline__ void cmask(f32x16& p0, f32x16& p1, int jb, int qrel, int hi) {
;     const float NEG = -INFINITY; const int kb = 64 * jb + 4 * hi;
; #pragma unroll
;     for (int r = 0; r < 16; ++r) { const int kv = kb + (r & 3) + 8 * (r >> 2); if (kv > qrel) p0[r] = NEG; if (kv + 32 > qrel) p1[r] = NEG; }
; }
.Lat_u1x_nodma:
	v_lshl_add_u64 v[126:127], v[126:127], 0, s[34:35]
	v_lshl_add_u64 v[14:15], v[14:15], 0, s[20:21]
	v_lshl_add_u64 v[124:125], v[124:125], 0, s[34:35]
	v_exp_f32_e32 v58, v58
	v_exp_f32_e32 v59, v59
	v_add_f32_e32 v157, v157, v58
	v_add_f32_e32 v157, v157, v59
	v_cvt_pk_bf16_f32 v53, v58, v59
	s_nop 1
	v_mfma_f32_32x32x16_bf16 v[16:31], v[68:71], v[200:203], v[16:31]
	v_exp_f32_e32 v60, v60
	v_exp_f32_e32 v61, v61
	v_add_f32_e32 v156, v156, v60
	v_add_f32_e32 v156, v156, v61
	v_cvt_pk_bf16_f32 v54, v60, v61
	s_nop 1
	v_mfma_f32_32x32x16_bf16 v[32:47], v[68:71], v[230:233], v[32:47]
	v_exp_f32_e32 v62, v62
	v_exp_f32_e32 v63, v63
	v_add_f32_e32 v157, v157, v62
	v_add_f32_e32 v157, v157, v63
	v_cvt_pk_bf16_f32 v55, v62, v63
	s_nop 1
	v_mfma_f32_32x32x16_bf16 v[16:31], v[48:51], v[204:207], v[16:31]
	v_mfma_f32_32x32x16_bf16 v[32:47], v[48:51], v[234:237], v[32:47]
	v_mfma_f32_32x32x16_bf16 v[16:31], v[52:55], v[208:211], v[16:31]
	v_mfma_f32_32x32x16_bf16 v[32:47], v[52:55], v[164:167], v[32:47]
	v_add_f32_e32 v156, v156, v157
	v_add_f32_e32 v128, v128, v156
	s_cmp_lt_u32 s52, s87
	s_cbranch_scc1 .Lat_u1x_nomask
	s_sub_i32 s4, s52, s87
	s_lshl_b32 s4, s4, 6
	s_nop 7
	s_nop 7
	v_lshl_add_u32 v147, v141, 2, s4
	v_sub_u32_e32 v147, v145, v147
	v_cmp_gt_i32_e32 vcc, 0, v147
	s_nop 1
	v_cndmask_b32_e32 v238, v238, v220, vcc
	v_cmp_gt_i32_e32 vcc, 1, v147
	s_nop 1
	v_cndmask_b32_e32 v239, v239, v220, vcc
	v_cmp_gt_i32_e32 vcc, 2, v147
	s_nop 1
	v_cndmask_b32_e32 v240, v240, v220, vcc
	v_cmp_gt_i32_e32 vcc, 3, v147
	s_nop 1
	v_cndmask_b32_e32 v241, v241, v220, vcc
	v_cmp_gt_i32_e32 vcc, 8, v147
	s_nop 1
	v_cndmask_b32_e32 v242, v242, v220, vcc
	v_cmp_gt_i32_e32 vcc, 9, v147
	s_nop 1
	v_cndmask_b32_e32 v243, v243, v220, vcc
	v_cmp_gt_i32_e32 vcc, 10, v147
	s_nop 1
	v_cndmask_b32_e32 v244, v244, v220, vcc
	v_cmp_gt_i32_e32 vcc, 11, v147
	s_nop 1
	v_cndmask_b32_e32 v245, v245, v220, vcc
	v_cmp_gt_i32_e32 vcc, 16, v147
	s_nop 1
	v_cndmask_b32_e32 v246, v246, v220, vcc
	v_cmp_gt_i32_e32 vcc, 17, v147
	s_nop 1
	v_cndmask_b32_e32 v247, v247, v220, vcc
	v_cmp_gt_i32_e32 vcc, 18, v147
	s_nop 1
	v_cndmask_b32_e32 v248, v248, v220, vcc
	v_cmp_gt_i32_e32 vcc, 19, v147
	s_nop 1
	v_cndmask_b32_e32 v249, v249, v220, vcc
	v_cmp_gt_i32_e32 vcc, 24, v147
	s_nop 1
	v_cndmask_b32_e32 v250, v250, v220, vcc
	v_cmp_gt_i32_e32 vcc, 25, v147
	s_nop 1
	v_cndmask_b32_e32 v251, v251, v220, vcc
	v_cmp_gt_i32_e32 vcc, 26, v147
	s_nop 1
	v_cndmask_b32_e32 v252, v252, v220, vcc
	v_cmp_gt_i32_e32 vcc, 27, v147
	s_nop 1
	v_cndmask_b32_e32 v253, v253, v220, vcc
	v_cmp_gt_i32_e32 vcc, 32, v147
	s_nop 1
	v_cndmask_b32_e32 v180, v180, v220, vcc
	v_cmp_gt_i32_e32 vcc, 33, v147
	s_nop 1
	v_cndmask_b32_e32 v181, v181, v220, vcc
	v_cmp_gt_i32_e32 vcc, 34, v147
	s_nop 1
	v_cndmask_b32_e32 v182, v182, v220, vcc
	v_cmp_gt_i32_e32 vcc, 35, v147
	s_nop 1
	v_cndmask_b32_e32 v183, v183, v220, vcc
	v_cmp_gt_i32_e32 vcc, 40, v147
	s_nop 1
	v_cndmask_b32_e32 v184, v184, v220, vcc
	v_cmp_gt_i32_e32 vcc, 41, v147
	s_nop 1
	v_cndmask_b32_e32 v185, v185, v220, vcc
	v_cmp_gt_i32_e32 vcc, 42, v147
	s_nop 1
	v_cndmask_b32_e32 v186, v186, v220, vcc
	v_cmp_gt_i32_e32 vcc, 43, v147
	s_nop 1
	v_cndmask_b32_e32 v187, v187, v220, vcc
	v_cmp_gt_i32_e32 vcc, 48, v147
	s_nop 1
	v_cndmask_b32_e32 v188, v188, v220, vcc
	v_cmp_gt_i32_e32 vcc, 49, v147
	s_nop 1
	v_cndmask_b32_e32 v189, v189, v220, vcc
	v_cmp_gt_i32_e32 vcc, 50, v147
	s_nop 1
	v_cndmask_b32_e32 v190, v190, v220, vcc
	v_cmp_gt_i32_e32 vcc, 51, v147
	s_nop 1
	v_cndmask_b32_e32 v191, v191, v220, vcc
	v_cmp_gt_i32_e32 vcc, 56, v147
	s_nop 1
	v_cndmask_b32_e32 v192, v192, v220, vcc
	v_cmp_gt_i32_e32 vcc, 57, v147
	s_nop 1
	v_cndmask_b32_e32 v193, v193, v220, vcc
	v_cmp_gt_i32_e32 vcc, 58, v147
	s_nop 1
	v_cndmask_b32_e32 v194, v194, v220, vcc
	v_cmp_gt_i32_e32 vcc, 59, v147
	s_nop 1
	v_cndmask_b32_e32 v195, v195, v220, vcc
.Lat_u1x_nomask:
	v_max3_f32 v129, v238, v239, v240
	v_max3_f32 v131, v241, v242, v243
	v_max3_f32 v129, v129, v244, v245
	v_max3_f32 v131, v131, v246, v247
	v_max3_f32 v129, v129, v248, v249
	v_max3_f32 v131, v131, v250, v251
	v_max3_f32 v129, v129, v252, v253
	v_max3_f32 v131, v131, v180, v181
	v_max3_f32 v129, v129, v182, v183
	v_max3_f32 v131, v131, v184, v185
	v_max3_f32 v129, v129, v186, v187
	v_max3_f32 v131, v131, v188, v189
	v_max3_f32 v129, v129, v190, v191
	v_max3_f32 v131, v131, v192, v193
	v_max3_f32 v129, v129, v194, v195
	v_max_f32_e32 v129, v129, v131
	v_cmp_lt_f32_e32 vcc, 0x41000000, v129
	s_cbranch_vccnz .Lat_u1x_rare

; #define SBAR() __builtin_amdgcn_sched_barrier(0)
; #define WAIT_BAR(N) asm volatile("s_waitcnt vmcnt(" #N ") lgkmcnt(0)\n\ts_barrier" ::: "memory")
; #define DMA_TILE(t, ks, vs) do { glds16(ksrc + (long)(t) * KVBLK * KNP, (unsigned)__builtin_amdgcn_readfirstlane(kdst + (ks) * KSLOT)); \
;         glds16(k2src + (long)(t) * KVBLK * KPP, (unsigned)__builtin_amdgcn_readfirstlane(k2dst + (ks) * KSLOT)); \
;         glds16(vsrc + (long)(t) * KVBLK * VP, (unsigned)__builtin_amdgcn_readfirstlane(vdst + (vs) * VSLOT)); } while (0)
; #define K_LOAD(ks) do { const LAS char* kp_ = kp0 + (ks) * KSLOT; \
;         _Pragma("unroll") for (int i_ = 0; i_ < 6; ++i_) { kf[2 * i_] = *(const LAS bf16x8*)(kp_ + i_ * 2048); kf[2 * i_ + 1] = *(const LAS bf16x8*)(kp_ + i_ * 2048 + 512); } SBAR(); } while (0)
; #define V_LOAD(vs) do { const LAS char* vp_ = vp0 + (vs) * VSLOT; \
;         _Pragma("unroll") for (int i_ = 0; i_ < 8; ++i_) { vlo[i_] = vtr(vp_ + ((i_ >> 2) * 4096 + (i_ & 3) * 1024)); vhi[i_] = vtr(vp_ + ((i_ >> 2) * 4096 + (i_ & 3) * 1024 + 512)); } SBAR(); } while (0)
; __device__ __forceinline__ void attn_unit(int b, int h, int qb, const bf16* Q, const bf16* __restrict__ Kn, const bf16* __restrict__ Kpe, const bf16* __restrict__ V, bf16* O, float* ASS, LAS char* shm) {
;     ...
;         for (int t = 0; t < NT; ++t) {
;             if (t + 1 < NT) { WAIT_BAR(3); } else { WAIT_BAR(0); }
;             if (t > 0) V_LOAD((vs + 3) & 3);
;             if (t + 2 < NT) DMA_TILE(t + 2, (ks == 0) ? 2 : ks - 1, (vs + 2) & 3);
;             SBAR();
;             if (t > 0) SOFTMAX();
;             K_LOAD(ks);
;             if (t > 0) PV_MMA();
;             QK_MMA(t);
;             ks = (ks == 2) ? 0 : ks + 1; vs = (vs + 1) & 3;
;         }
.Lat_u1x_end:
	s_cmp_eq_u32 s52, s86
	s_cbranch_scc1 .Lat_u1_tail
	s_add_i32 s4, s52, 1
	s_cmp_ge_u32 s4, s86
	s_cbranch_scc1 .Lat_u1y_lw
	s_waitcnt vmcnt(3) lgkmcnt(0)
	s_branch .Lat_u1y_bar

; #define SBAR() __builtin_amdgcn_sched_barrier(0)
; #define WAIT_BAR(N) asm volatile("s_waitcnt vmcnt(" #N ") lgkmcnt(0)\n\ts_barrier" ::: "memory")
; #define DMA_TILE(t, ks, vs) do { glds16(ksrc + (long)(t) * KVBLK * KNP, (unsigned)__builtin_amdgcn_readfirstlane(kdst + (ks) * KSLOT)); \
;         glds16(k2src + (long)(t) * KVBLK * KPP, (unsigned)__builtin_amdgcn_readfirstlane(k2dst + (ks) * KSLOT)); \
;         glds16(vsrc + (long)(t) * KVBLK * VP, (unsigned)__builtin_amdgcn_readfirstlane(vdst + (vs) * VSLOT)); } while (0)
; #define K_LOAD(ks) do { const LAS char* kp_ = kp0 + (ks) * KSLOT; \
;         _Pragma("unroll") for (int i_ = 0; i_ < 6; ++i_) { kf[2 * i_] = *(const LAS bf16x8*)(kp_ + i_ * 2048); kf[2 * i_ + 1] = *(const LAS bf16x8*)(kp_ + i_ * 2048 + 512); } SBAR(); } while (0)
; #define V_LOAD(vs) do { const LAS char* vp_ = vp0 + (vs) * VSLOT; \
;         _Pragma("unroll") for (int i_ = 0; i_ < 8; ++i_) { vlo[i_] = vtr(vp_ + ((i_ >> 2) * 4096 + (i_ & 3) * 1024)); vhi[i_] = vtr(vp_ + ((i_ >> 2) * 4096 + (i_ & 3) * 1024 + 512)); } SBAR(); } while (0)
; __device__ __forceinline__ void attn_unit(int b, int h, int qb, const bf16* Q, const bf16* __restrict__ Kn, const bf16* __restrict__ Kpe, const bf16* __restrict__ V, bf16* O, float* ASS, LAS char* shm) {
;     ...
;         for (int t = 0; t < NT; ++t) {
;             if (t + 1 < NT) { WAIT_BAR(3); } else { WAIT_BAR(0); }
;             if (t > 0) V_LOAD((vs + 3) & 3);
;             if (t + 2 < NT) DMA_TILE(t + 2, (ks == 0) ? 2 : ks - 1, (vs + 2) & 3);
;             SBAR();
;             if (t > 0) SOFTMAX();
;             K_LOAD(ks);
;             if (t > 0) PV_MMA();
;             QK_MMA(t);
.Lat_u1y_bar:
	s_barrier
	s_lshr_b32 s4, s69, 1
	s_sub_u32 s4, s52, s4
	s_cmp_gt_i32 s4, s87
	s_cbranch_scc1 .Lat_u1y_noqk
	s_mul_i32 s53, s48, 0x3000
	v_add_u32_e32 v158, s53, v146
	ds_read_b128 v[196:199], v158
	ds_read_b128 v[200:203], v158 offset:512
	ds_read_b128 v[204:207], v158 offset:2048
	ds_read_b128 v[208:211], v158 offset:2560
	ds_read_b128 v[212:215], v158 offset:4096
	ds_read_b128 v[230:233], v158 offset:4608
	ds_read_b128 v[234:237], v158 offset:6144
	ds_read_b128 v[164:167], v158 offset:6656
	ds_read_b128 v[168:171], v158 offset:8192
	ds_read_b128 v[172:175], v158 offset:8704
	ds_read_b128 v[148:151], v158 offset:10240
	ds_read_b128 v[152:155], v158 offset:10752
	s_lshl_b32 s4, s50, 13
	s_add_i32 s4, s4, 0x6000
	s_and_b32 s4, s4, 0x6000
	v_add_u32_e32 v159, s4, v144
	v_mov_b32_e32 v156, 0
	v_mov_b32_e32 v157, 0
	s_waitcnt lgkmcnt(11)
	v_mfma_f32_32x32x16_bf16 v[64:79], v[196:199], v[100:103], v[104:119]
	ds_read_b64_tr_b16 v[196:197], v159 offset:36864
	ds_read_b64_tr_b16 v[198:199], v159 offset:37376
	v_exp_f32_e32 v238, v238
	v_exp_f32_e32 v239, v239
	v_add_f32_e32 v156, v156, v238
	v_add_f32_e32 v156, v156, v239
	v_cvt_pk_bf16_f32 v238, v238, v239
	s_waitcnt lgkmcnt(12)
	v_mfma_f32_32x32x16_bf16 v[48:63], v[200:203], v[100:103], v[104:119]
	ds_read_b64_tr_b16 v[200:201], v159 offset:37888
	ds_read_b64_tr_b16 v[202:203], v159 offset:38400
	v_exp_f32_e32 v240, v240
	v_exp_f32_e32 v241, v241
	v_add_f32_e32 v157, v157, v240
	v_add_f32_e32 v157, v157, v241
	v_cvt_pk_bf16_f32 v239, v240, v241
	s_waitcnt lgkmcnt(13)
	v_mfma_f32_32x32x16_bf16 v[64:79], v[204:207], v[96:99], v[64:79]
	ds_read_b64_tr_b16 v[204:205], v159 offset:38912
	ds_read_b64_tr_b16 v[206:207], v159 offset:39424
	v_exp_f32_e32 v242, v242
	v_exp_f32_e32 v243, v243
	v_add_f32_e32 v156, v156, v242
	v_add_f32_e32 v156, v156, v243
	v_cvt_pk_bf16_f32 v240, v242, v243
	s_waitcnt lgkmcnt(14)
	v_mfma_f32_32x32x16_bf16 v[48:63], v[208:211], v[96:99], v[48:63]
	ds_read_b64_tr_b16 v[208:209], v159 offset:39936
	ds_read_b64_tr_b16 v[210:211], v159 offset:40448
	v_exp_f32_e32 v244, v244
	v_exp_f32_e32 v245, v245
	v_add_f32_e32 v157, v157, v244
	v_add_f32_e32 v157, v157, v245
	v_cvt_pk_bf16_f32 v241, v244, v245
	s_waitcnt lgkmcnt(15)
	v_mfma_f32_32x32x16_bf16 v[64:79], v[212:215], v[92:95], v[64:79]
	ds_read_b64_tr_b16 v[212:213], v159 offset:40960
	ds_read_b64_tr_b16 v[214:215], v159 offset:41472
	v_exp_f32_e32 v246, v246
	v_exp_f32_e32 v247, v247
	v_add_f32_e32 v156, v156, v246
	v_add_f32_e32 v156, v156, v247
	v_cvt_pk_bf16_f32 v242, v246, v247
	s_waitcnt lgkmcnt(15)
	v_mfma_f32_32x32x16_bf16 v[48:63], v[230:233], v[92:95], v[48:63]
	ds_read_b64_tr_b16 v[230:231], v159 offset:41984
	ds_read_b64_tr_b16 v[232:233], v159 offset:42496
	v_exp_f32_e32 v248, v248
	v_exp_f32_e32 v249, v249
	v_add_f32_e32 v157, v157, v248
	v_add_f32_e32 v157, v157, v249
	v_cvt_pk_bf16_f32 v243, v248, v249
	s_waitcnt lgkmcnt(15)
	v_mfma_f32_32x32x16_bf16 v[64:79], v[234:237], v[88:91], v[64:79]
	ds_read_b64_tr_b16 v[234:235], v159 offset:43008
	ds_read_b64_tr_b16 v[236:237], v159 offset:43520
	v_exp_f32_e32 v250, v250
	v_exp_f32_e32 v251, v251
	v_add_f32_e32 v156, v156, v250
	v_add_f32_e32 v156, v156, v251
	v_cvt_pk_bf16_f32 v244, v250, v251
	s_waitcnt lgkmcnt(15)
	v_mfma_f32_32x32x16_bf16 v[48:63], v[164:167], v[88:91], v[48:63]
	ds_read_b64_tr_b16 v[164:165], v159 offset:44032
	ds_read_b64_tr_b16 v[166:167], v159 offset:44544
	v_exp_f32_e32 v252, v252
	v_exp_f32_e32 v253, v253
	v_add_f32_e32 v157, v157, v252
	v_add_f32_e32 v157, v157, v253
	v_cvt_pk_bf16_f32 v245, v252, v253
	s_waitcnt lgkmcnt(15)
	v_mfma_f32_32x32x16_bf16 v[64:79], v[168:171], v[84:87], v[64:79]
	v_exp_f32_e32 v180, v180
	v_exp_f32_e32 v181, v181
	v_add_f32_e32 v156, v156, v180
	v_add_f32_e32 v156, v156, v181
	v_cvt_pk_bf16_f32 v180, v180, v181
	s_waitcnt lgkmcnt(15)
	v_mfma_f32_32x32x16_bf16 v[48:63], v[172:175], v[84:87], v[48:63]
	v_exp_f32_e32 v182, v182
	v_exp_f32_e32 v183, v183
	v_add_f32_e32 v157, v157, v182
	v_add_f32_e32 v157, v157, v183
	v_cvt_pk_bf16_f32 v181, v182, v183
	s_waitcnt lgkmcnt(15)
	v_mfma_f32_32x32x16_bf16 v[64:79], v[148:151], v[80:83], v[64:79]
	v_exp_f32_e32 v184, v184
	v_exp_f32_e32 v185, v185
	v_add_f32_e32 v156, v156, v184
	v_add_f32_e32 v156, v156, v185
	v_cvt_pk_bf16_f32 v182, v184, v185
	s_waitcnt lgkmcnt(15)
	v_mfma_f32_32x32x16_bf16 v[48:63], v[152:155], v[80:83], v[48:63]
	v_exp_f32_e32 v186, v186
	v_exp_f32_e32 v187, v187
	v_add_f32_e32 v157, v157, v186
	v_add_f32_e32 v157, v157, v187
	v_cvt_pk_bf16_f32 v183, v186, v187
	s_nop 1
	s_waitcnt lgkmcnt(0)
	v_mfma_f32_32x32x16_bf16 v[16:31], v[238:241], v[196:199], v[16:31]
	v_exp_f32_e32 v188, v188
	v_exp_f32_e32 v189, v189
	v_add_f32_e32 v156, v156, v188
	v_add_f32_e32 v156, v156, v189
	v_cvt_pk_bf16_f32 v184, v188, v189
	s_nop 1
	v_mfma_f32_32x32x16_bf16 v[32:47], v[238:241], v[212:215], v[32:47]
	s_mul_i32 s53, s48, 0x3000
	s_add_i32 s4, s52, 2
	s_cmp_ge_u32 s4, s86
	s_cbranch_scc1 .Lat_u1y_nodma
	s_add_i32 s4, s53, 0xffffd000
	s_cmp_lg_u32 s48, 0
	s_cselect_b32 s4, s4, 0x6000
	s_add_i32 s5, s4, s97
	s_mov_b32 m0, s5
	s_add_i32 s4, s4, s72
	global_load_lds_dwordx4 v[126:127], off
	s_mov_b32 m0, s4
	s_lshl_b32 s5, s50, 13
	global_load_lds_dwordx4 v[14:15], off
	s_xor_b32 s5, s5, 0x4000
	s_add_i32 s5, s5, s73
	s_mov_b32 m0, s5
	s_nop 0
	global_load_lds_dwordx4 v[124:125], off
; __device__ __forceinline__ void cmask(f32x16& p0, f32x16& p1, int jb, int qrel, int hi) {
;     const float NEG = -INFINITY; const int kb = 64 * jb + 4 * hi;
; #pragma unroll
;     for (int r = 0; r < 16; ++r) { const int kv = kb + (r & 3) + 8 * (r >> 2); if (kv > qrel) p0[r] = NEG; if (kv + 32 > qrel) p1[r] = NEG; }
; }
; __device__ __forceinline__ void glds16(const void* gsrc, unsigned lds_dst) { unsigned keep;
;     asm volatile("s_mov_b32 %0, m0\n\ts_mov_b32 m0, %2\n\ts_nop 0\n\tglobal_load_lds_dwordx4 %1, off\n\ts_mov_b32 m0, %0" : "=&s"(keep) : "v"(gsrc), "s"(lds_dst) : "memory"); }
; __device__ __forceinline__ float max3f(float a, float b, float c) { return __builtin_fmaxf(__builtin_fmaxf(a, b), c); }
; __device__ __forceinline__ float rowmax(const f32x16& p0, const f32x16& p1) {
;     float a = max3f(p0[0], p0[1], p1[0]), b = max3f(p0[2], p0[3], p1[1]); a = max3f(a, p1[2], p1[3]);
; #pragma unroll
;     for (int r = 4; r < 16; r += 4) { a = max3f(a, p0[r], p0[r + 1]); b = max3f(b, p0[r + 2], p0[r + 3]); a = max3f(a, p1[r], p1[r + 1]); b = max3f(b, p1[r + 2], p1[r + 3]); }
;     const float m = __builtin_fmaxf(a, b);
;     auto rr = __builtin_amdgcn_permlane32_swap(__float_as_uint(m), __float_as_uint(m), false, false);
;     return __builtin_fmaxf(__uint_as_float(rr[0]), __uint_as_float(rr[1]));
; }
.Lat_u1y_nodma:
	v_lshl_add_u64 v[126:127], v[126:127], 0, s[34:35]
	v_lshl_add_u64 v[14:15], v[14:15], 0, s[20:21]
	v_lshl_add_u64 v[124:125], v[124:125], 0, s[34:35]
	v_exp_f32_e32 v190, v190
	v_exp_f32_e32 v191, v191
	v_add_f32_e32 v157, v157, v190
	v_add_f32_e32 v157, v157, v191
	v_cvt_pk_bf16_f32 v185, v190, v191
	s_nop 1
	v_mfma_f32_32x32x16_bf16 v[16:31], v[242:245], v[200:203], v[16:31]
	v_exp_f32_e32 v192, v192
	v_exp_f32_e32 v193, v193
	v_add_f32_e32 v156, v156, v192
	v_add_f32_e32 v156, v156, v193
	v_cvt_pk_bf16_f32 v186, v192, v193
	s_nop 1
	v_mfma_f32_32x32x16_bf16 v[32:47], v[242:245], v[230:233], v[32:47]
	v_exp_f32_e32 v194, v194
	v_exp_f32_e32 v195, v195
	v_add_f32_e32 v157, v157, v194
	v_add_f32_e32 v157, v157, v195
	v_cvt_pk_bf16_f32 v187, v194, v195
	s_nop 1
	v_mfma_f32_32x32x16_bf16 v[16:31], v[180:183], v[204:207], v[16:31]
	v_mfma_f32_32x32x16_bf16 v[32:47], v[180:183], v[234:237], v[32:47]
	v_mfma_f32_32x32x16_bf16 v[16:31], v[184:187], v[208:211], v[16:31]
	v_mfma_f32_32x32x16_bf16 v[32:47], v[184:187], v[164:167], v[32:47]
	v_add_f32_e32 v156, v156, v157
	v_add_f32_e32 v128, v128, v156
	s_cmp_lt_u32 s52, s87
	s_cbranch_scc1 .Lat_u1y_nomask
	s_sub_i32 s4, s52, s87
	s_lshl_b32 s4, s4, 6
	s_nop 7
	s_nop 7
	v_lshl_add_u32 v147, v141, 2, s4
	v_sub_u32_e32 v147, v145, v147
	v_cmp_gt_i32_e32 vcc, 0, v147
	s_nop 1
	v_cndmask_b32_e32 v64, v64, v220, vcc
	v_cmp_gt_i32_e32 vcc, 1, v147
	s_nop 1
	v_cndmask_b32_e32 v65, v65, v220, vcc
	v_cmp_gt_i32_e32 vcc, 2, v147
	s_nop 1
	v_cndmask_b32_e32 v66, v66, v220, vcc
	v_cmp_gt_i32_e32 vcc, 3, v147
	s_nop 1
	v_cndmask_b32_e32 v67, v67, v220, vcc
	v_cmp_gt_i32_e32 vcc, 8, v147
	s_nop 1
	v_cndmask_b32_e32 v68, v68, v220, vcc
	v_cmp_gt_i32_e32 vcc, 9, v147
	s_nop 1
	v_cndmask_b32_e32 v69, v69, v220, vcc
	v_cmp_gt_i32_e32 vcc, 10, v147
	s_nop 1
	v_cndmask_b32_e32 v70, v70, v220, vcc
	v_cmp_gt_i32_e32 vcc, 11, v147
	s_nop 1
	v_cndmask_b32_e32 v71, v71, v220, vcc
	v_cmp_gt_i32_e32 vcc, 16, v147
	s_nop 1
	v_cndmask_b32_e32 v72, v72, v220, vcc
	v_cmp_gt_i32_e32 vcc, 17, v147
	s_nop 1
	v_cndmask_b32_e32 v73, v73, v220, vcc
	v_cmp_gt_i32_e32 vcc, 18, v147
	s_nop 1
	v_cndmask_b32_e32 v74, v74, v220, vcc
	v_cmp_gt_i32_e32 vcc, 19, v147
	s_nop 1
	v_cndmask_b32_e32 v75, v75, v220, vcc
	v_cmp_gt_i32_e32 vcc, 24, v147
	s_nop 1
	v_cndmask_b32_e32 v76, v76, v220, vcc
	v_cmp_gt_i32_e32 vcc, 25, v147
	s_nop 1
	v_cndmask_b32_e32 v77, v77, v220, vcc
	v_cmp_gt_i32_e32 vcc, 26, v147
	s_nop 1
	v_cndmask_b32_e32 v78, v78, v220, vcc
	v_cmp_gt_i32_e32 vcc, 27, v147
	s_nop 1
	v_cndmask_b32_e32 v79, v79, v220, vcc
	v_cmp_gt_i32_e32 vcc, 32, v147
	s_nop 1
	v_cndmask_b32_e32 v48, v48, v220, vcc
	v_cmp_gt_i32_e32 vcc, 33, v147
	s_nop 1
	v_cndmask_b32_e32 v49, v49, v220, vcc
	v_cmp_gt_i32_e32 vcc, 34, v147
	s_nop 1
	v_cndmask_b32_e32 v50, v50, v220, vcc
	v_cmp_gt_i32_e32 vcc, 35, v147
	s_nop 1
	v_cndmask_b32_e32 v51, v51, v220, vcc
	v_cmp_gt_i32_e32 vcc, 40, v147
	s_nop 1
	v_cndmask_b32_e32 v52, v52, v220, vcc
	v_cmp_gt_i32_e32 vcc, 41, v147
	s_nop 1
	v_cndmask_b32_e32 v53, v53, v220, vcc
	v_cmp_gt_i32_e32 vcc, 42, v147
	s_nop 1
	v_cndmask_b32_e32 v54, v54, v220, vcc
	v_cmp_gt_i32_e32 vcc, 43, v147
	s_nop 1
	v_cndmask_b32_e32 v55, v55, v220, vcc
	v_cmp_gt_i32_e32 vcc, 48, v147
	s_nop 1
	v_cndmask_b32_e32 v56, v56, v220, vcc
	v_cmp_gt_i32_e32 vcc, 49, v147
	s_nop 1
	v_cndmask_b32_e32 v57, v57, v220, vcc
	v_cmp_gt_i32_e32 vcc, 50, v147
	s_nop 1
	v_cndmask_b32_e32 v58, v58, v220, vcc
	v_cmp_gt_i32_e32 vcc, 51, v147
	s_nop 1
	v_cndmask_b32_e32 v59, v59, v220, vcc
	v_cmp_gt_i32_e32 vcc, 56, v147
	s_nop 1
	v_cndmask_b32_e32 v60, v60, v220, vcc
	v_cmp_gt_i32_e32 vcc, 57, v147
	s_nop 1
	v_cndmask_b32_e32 v61, v61, v220, vcc
	v_cmp_gt_i32_e32 vcc, 58, v147
	s_nop 1
	v_cndmask_b32_e32 v62, v62, v220, vcc
	v_cmp_gt_i32_e32 vcc, 59, v147
	s_nop 1
	v_cndmask_b32_e32 v63, v63, v220, vcc
.Lat_u1y_nomask:
	v_max3_f32 v129, v64, v65, v66
	v_max3_f32 v131, v67, v68, v69
	v_max3_f32 v129, v129, v70, v71
	v_max3_f32 v131, v131, v72, v73
	v_max3_f32 v129, v129, v74, v75
	v_max3_f32 v131, v131, v76, v77
	v_max3_f32 v129, v129, v78, v79
	v_max3_f32 v131, v131, v48, v49
	v_max3_f32 v129, v129, v50, v51
	v_max3_f32 v131, v131, v52, v53
	v_max3_f32 v129, v129, v54, v55
	v_max3_f32 v131, v131, v56, v57
	v_max3_f32 v129, v129, v58, v59
	v_max3_f32 v131, v131, v60, v61
	v_max3_f32 v129, v129, v62, v63
	v_max_f32_e32 v129, v129, v131
	v_cmp_lt_f32_e32 vcc, 0x41000000, v129
	s_cbranch_vccnz .Lat_u1y_rare
.Lat_u1y_back:
	s_add_i32 s52, s52, 1
	s_add_i32 s4, s48, 1
	s_cmp_lg_u32 s48, 2
	s_cselect_b32 s48, s4, 0
	s_add_i32 s50, s50, 1
	s_and_b32 s50, s50, 3
.Lat_u1y_end:
	s_branch .Lat_u1_loop
; #define V_LOAD(vs) do { const LAS char* vp_ = vp0 + (vs) * VSLOT; \
;         _Pragma("unroll") for (int i_ = 0; i_ < 8; ++i_) { vlo[i_] = vtr(vp_ + ((i_ >> 2) * 4096 + (i_ & 3) * 1024)); vhi[i_] = vtr(vp_ + ((i_ >> 2) * 4096 + (i_ & 3) * 1024 + 512)); } SBAR(); } while (0)
; __device__ __forceinline__ void attn_unit(int b, int h, int qb, const bf16* Q, const bf16* __restrict__ Kn, const bf16* __restrict__ Kpe, const bf16* __restrict__ V, bf16* O, float* ASS, LAS char* shm) {
;     ...
;         V_LOAD((vs + 3) & 3);
;         SOFTMAX();
;         PV_MMA();
.Lat_u1_tail:
	s_waitcnt lgkmcnt(0)
	s_lshr_b32 s4, s69, 1
	s_sub_u32 s4, s52, s4
	s_sub_u32 s4, s4, 1
	s_cmp_gt_i32 s4, s87
	s_cbranch_scc1 .Lat_u1t_skip
	s_lshl_b32 s4, s50, 13
	s_add_i32 s4, s4, 0x6000
	s_and_b32 s4, s4, 0x6000
	v_add_u32_e32 v159, s4, v144
	ds_read_b64_tr_b16 v[196:197], v159 offset:36864
	ds_read_b64_tr_b16 v[198:199], v159 offset:37376
	ds_read_b64_tr_b16 v[200:201], v159 offset:37888
	ds_read_b64_tr_b16 v[202:203], v159 offset:38400
	ds_read_b64_tr_b16 v[204:205], v159 offset:38912
	ds_read_b64_tr_b16 v[206:207], v159 offset:39424
	ds_read_b64_tr_b16 v[208:209], v159 offset:39936
	ds_read_b64_tr_b16 v[210:211], v159 offset:40448
	ds_read_b64_tr_b16 v[212:213], v159 offset:40960
	ds_read_b64_tr_b16 v[214:215], v159 offset:41472
	ds_read_b64_tr_b16 v[230:231], v159 offset:41984
	ds_read_b64_tr_b16 v[232:233], v159 offset:42496
	ds_read_b64_tr_b16 v[234:235], v159 offset:43008
	ds_read_b64_tr_b16 v[236:237], v159 offset:43520
	ds_read_b64_tr_b16 v[164:165], v159 offset:44032
	ds_read_b64_tr_b16 v[166:167], v159 offset:44544
	v_mov_b32_e32 v156, 0
	v_mov_b32_e32 v157, 0
	v_exp_f32_e32 v238, v238
	v_exp_f32_e32 v239, v239
	v_add_f32_e32 v156, v156, v238
	v_add_f32_e32 v156, v156, v239
	v_cvt_pk_bf16_f32 v238, v238, v239
	v_exp_f32_e32 v240, v240
	v_exp_f32_e32 v241, v241
	v_add_f32_e32 v157, v157, v240
	v_add_f32_e32 v157, v157, v241
	v_cvt_pk_bf16_f32 v239, v240, v241
	v_exp_f32_e32 v242, v242
	v_exp_f32_e32 v243, v243
	v_add_f32_e32 v156, v156, v242
	v_add_f32_e32 v156, v156, v243
	v_cvt_pk_bf16_f32 v240, v242, v243
	v_exp_f32_e32 v244, v244
	v_exp_f32_e32 v245, v245
	v_add_f32_e32 v157, v157, v244
	v_add_f32_e32 v157, v157, v245
	v_cvt_pk_bf16_f32 v241, v244, v245
	v_exp_f32_e32 v246, v246
	v_exp_f32_e32 v247, v247
	v_add_f32_e32 v156, v156, v246
	v_add_f32_e32 v156, v156, v247
	v_cvt_pk_bf16_f32 v242, v246, v247
	v_exp_f32_e32 v248, v248
	v_exp_f32_e32 v249, v249
	v_add_f32_e32 v157, v157, v248
	v_add_f32_e32 v157, v157, v249
	v_cvt_pk_bf16_f32 v243, v248, v249
	v_exp_f32_e32 v250, v250
	v_exp_f32_e32 v251, v251
	v_add_f32_e32 v156, v156, v250
	v_add_f32_e32 v156, v156, v251
	v_cvt_pk_bf16_f32 v244, v250, v251
	v_exp_f32_e32 v252, v252
	v_exp_f32_e32 v253, v253
	v_add_f32_e32 v157, v157, v252
	v_add_f32_e32 v157, v157, v253
	v_cvt_pk_bf16_f32 v245, v252, v253
	v_exp_f32_e32 v180, v180
	v_exp_f32_e32 v181, v181
	v_add_f32_e32 v156, v156, v180
	v_add_f32_e32 v156, v156, v181
	v_cvt_pk_bf16_f32 v180, v180, v181
	v_exp_f32_e32 v182, v182
	v_exp_f32_e32 v183, v183
	v_add_f32_e32 v157, v157, v182
	v_add_f32_e32 v157, v157, v183
	v_cvt_pk_bf16_f32 v181, v182, v183
	v_exp_f32_e32 v184, v184
	v_exp_f32_e32 v185, v185
	v_add_f32_e32 v156, v156, v184
	v_add_f32_e32 v156, v156, v185
	v_cvt_pk_bf16_f32 v182, v184, v185
	v_exp_f32_e32 v186, v186
	v_exp_f32_e32 v187, v187
	v_add_f32_e32 v157, v157, v186
	v_add_f32_e32 v157, v157, v187
	v_cvt_pk_bf16_f32 v183, v186, v187
	v_exp_f32_e32 v188, v188
	v_exp_f32_e32 v189, v189
	v_add_f32_e32 v156, v156, v188
	v_add_f32_e32 v156, v156, v189
	v_cvt_pk_bf16_f32 v184, v188, v189
	v_exp_f32_e32 v190, v190
	v_exp_f32_e32 v191, v191
	v_add_f32_e32 v157, v157, v190
	v_add_f32_e32 v157, v157, v191
	v_cvt_pk_bf16_f32 v185, v190, v191
	v_exp_f32_e32 v192, v192
	v_exp_f32_e32 v193, v193
	v_add_f32_e32 v156, v156, v192
	v_add_f32_e32 v156, v156, v193
	v_cvt_pk_bf16_f32 v186, v192, v193
	v_exp_f32_e32 v194, v194
	v_exp_f32_e32 v195, v195
	v_add_f32_e32 v157, v157, v194
	v_add_f32_e32 v157, v157, v195
	v_cvt_pk_bf16_f32 v187, v194, v195
	v_add_f32_e32 v156, v156, v157
	v_add_f32_e32 v128, v128, v156
	s_waitcnt lgkmcnt(0)
	v_mfma_f32_32x32x16_bf16 v[16:31], v[238:241], v[196:199], v[16:31]
	v_mfma_f32_32x32x16_bf16 v[32:47], v[238:241], v[212:215], v[32:47]
	v_mfma_f32_32x32x16_bf16 v[16:31], v[242:245], v[200:203], v[16:31]
	v_mfma_f32_32x32x16_bf16 v[32:47], v[242:245], v[230:233], v[32:47]
	v_mfma_f32_32x32x16_bf16 v[16:31], v[180:183], v[204:207], v[16:31]
	v_mfma_f32_32x32x16_bf16 v[32:47], v[180:183], v[234:237], v[32:47]
	v_mfma_f32_32x32x16_bf16 v[16:31], v[184:187], v[208:211], v[16:31]
	v_mfma_f32_32x32x16_bf16 v[32:47], v[184:187], v[164:167], v[32:47]
.Lat_u1t_skip:
	s_mov_b32 m0, s54
	v_mov_b32_e32 v14, v128
	s_mov_b64 s[46:47], 0
	s_branch .LBB0_889
; __device__ __forceinline__ float rowmax(const f32x16& p0, const f32x16& p1) {
;     ...
;     auto rr = __builtin_amdgcn_permlane32_swap(__float_as_uint(m), __float_as_uint(m), false, false);
;     return __builtin_fmaxf(__uint_as_float(rr[0]), __uint_as_float(rr[1]));
.Lat_u1x_rare:
	s_nop 15
	v_mov_b32_e32 v131, v129
	s_nop 1
	v_permlane32_swap_b32_e32 v129, v131
	s_nop 0
	v_max_f32_e32 v129, v129, v131
	v_max_f32_e32 v131, 0, v129
	v_exp_f32_e64 v147, -v131
	v_add_f32_e32 v130, v130, v131
	s_nop 0
	s_and_saveexec_b64 s[46:47], s[38:39]
	ds_write_b32 v142, v147
	s_or_b64 exec, exec, s[46:47]
	v_mul_f32_e32 v128, v128, v147
	v_sub_f32_e32 v104, v104, v131
	v_sub_f32_e32 v105, v105, v131
	v_sub_f32_e32 v106, v106, v131
	v_sub_f32_e32 v107, v107, v131
	v_sub_f32_e32 v108, v108, v131
	v_sub_f32_e32 v109, v109, v131
	v_sub_f32_e32 v110, v110, v131
	v_sub_f32_e32 v111, v111, v131
	v_sub_f32_e32 v112, v112, v131
	v_sub_f32_e32 v113, v113, v131
	v_sub_f32_e32 v114, v114, v131
	v_sub_f32_e32 v115, v115, v131
	v_sub_f32_e32 v116, v116, v131
	v_sub_f32_e32 v117, v117, v131
	v_sub_f32_e32 v118, v118, v131
	v_sub_f32_e32 v119, v119, v131
	v_sub_f32_e32 v238, v238, v131
	v_sub_f32_e32 v239, v239, v131
	v_sub_f32_e32 v240, v240, v131
	v_sub_f32_e32 v241, v241, v131
	v_sub_f32_e32 v242, v242, v131
	v_sub_f32_e32 v243, v243, v131
	v_sub_f32_e32 v244, v244, v131
	v_sub_f32_e32 v245, v245, v131
	v_sub_f32_e32 v246, v246, v131
	v_sub_f32_e32 v247, v247, v131
	v_sub_f32_e32 v248, v248, v131
	v_sub_f32_e32 v249, v249, v131
	v_sub_f32_e32 v250, v250, v131
	v_sub_f32_e32 v251, v251, v131
	v_sub_f32_e32 v252, v252, v131
	v_sub_f32_e32 v253, v253, v131
	v_sub_f32_e32 v180, v180, v131
	v_sub_f32_e32 v181, v181, v131
	v_sub_f32_e32 v182, v182, v131
	v_sub_f32_e32 v183, v183, v131
	v_sub_f32_e32 v184, v184, v131
	v_sub_f32_e32 v185, v185, v131
	v_sub_f32_e32 v186, v186, v131
	v_sub_f32_e32 v187, v187, v131
	v_sub_f32_e32 v188, v188, v131
	v_sub_f32_e32 v189, v189, v131
	v_sub_f32_e32 v190, v190, v131
	v_sub_f32_e32 v191, v191, v131
	v_sub_f32_e32 v192, v192, v131
	v_sub_f32_e32 v193, v193, v131
	v_sub_f32_e32 v194, v194, v131
	v_sub_f32_e32 v195, v195, v131
	s_waitcnt lgkmcnt(0)
	v_add_u32_e32 v147, s96, v143
	ds_read_b128 v[2:5], v147
	ds_read_b128 v[6:9], v147 offset:32
	ds_read_b128 v[10:13], v147 offset:64
	ds_read_b128 v[120:123], v147 offset:96
	s_waitcnt lgkmcnt(0)
	v_mul_f32_e32 v16, v16, v2
	v_mul_f32_e32 v32, v32, v2
	v_mul_f32_e32 v17, v17, v3
	v_mul_f32_e32 v33, v33, v3
	v_mul_f32_e32 v18, v18, v4
	v_mul_f32_e32 v34, v34, v4
	v_mul_f32_e32 v19, v19, v5
	v_mul_f32_e32 v35, v35, v5
	v_mul_f32_e32 v20, v20, v6
	v_mul_f32_e32 v36, v36, v6
	v_mul_f32_e32 v21, v21, v7
	v_mul_f32_e32 v37, v37, v7
	v_mul_f32_e32 v22, v22, v8
	v_mul_f32_e32 v38, v38, v8
	v_mul_f32_e32 v23, v23, v9
	v_mul_f32_e32 v39, v39, v9
	v_mul_f32_e32 v24, v24, v10
	v_mul_f32_e32 v40, v40, v10
	v_mul_f32_e32 v25, v25, v11
	v_mul_f32_e32 v41, v41, v11
	v_mul_f32_e32 v26, v26, v12
	v_mul_f32_e32 v42, v42, v12
	v_mul_f32_e32 v27, v27, v13
	v_mul_f32_e32 v43, v43, v13
	v_mul_f32_e32 v28, v28, v120
	v_mul_f32_e32 v44, v44, v120
	v_mul_f32_e32 v29, v29, v121
	v_mul_f32_e32 v45, v45, v121
	v_mul_f32_e32 v30, v30, v122
	v_mul_f32_e32 v46, v46, v122
	v_mul_f32_e32 v31, v31, v123
	v_mul_f32_e32 v47, v47, v123
	s_branch .Lat_u1x_back
.Lat_u1y_rare:
	s_nop 15
	v_mov_b32_e32 v131, v129
	s_nop 1
	v_permlane32_swap_b32_e32 v129, v131
	s_nop 0
	v_max_f32_e32 v129, v129, v131
	v_max_f32_e32 v131, 0, v129
	v_exp_f32_e64 v147, -v131
	v_add_f32_e32 v130, v130, v131
	s_nop 0
	s_and_saveexec_b64 s[46:47], s[38:39]
	ds_write_b32 v142, v147
	s_or_b64 exec, exec, s[46:47]
	v_mul_f32_e32 v128, v128, v147
	v_sub_f32_e32 v104, v104, v131
	v_sub_f32_e32 v105, v105, v131
	v_sub_f32_e32 v106, v106, v131
	v_sub_f32_e32 v107, v107, v131
	v_sub_f32_e32 v108, v108, v131
	v_sub_f32_e32 v109, v109, v131
	v_sub_f32_e32 v110, v110, v131
	v_sub_f32_e32 v111, v111, v131
	v_sub_f32_e32 v112, v112, v131
	v_sub_f32_e32 v113, v113, v131
	v_sub_f32_e32 v114, v114, v131
	v_sub_f32_e32 v115, v115, v131
	v_sub_f32_e32 v116, v116, v131
	v_sub_f32_e32 v117, v117, v131
	v_sub_f32_e32 v118, v118, v131
	v_sub_f32_e32 v119, v119, v131
	v_sub_f32_e32 v64, v64, v131
	v_sub_f32_e32 v65, v65, v131
	v_sub_f32_e32 v66, v66, v131
	v_sub_f32_e32 v67, v67, v131
	v_sub_f32_e32 v68, v68, v131
	v_sub_f32_e32 v69, v69, v131
	v_sub_f32_e32 v70, v70, v131
	v_sub_f32_e32 v71, v71, v131
	v_sub_f32_e32 v72, v72, v131
	v_sub_f32_e32 v73, v73, v131
	v_sub_f32_e32 v74, v74, v131
	v_sub_f32_e32 v75, v75, v131
	v_sub_f32_e32 v76, v76, v131
	v_sub_f32_e32 v77, v77, v131
	v_sub_f32_e32 v78, v78, v131
	v_sub_f32_e32 v79, v79, v131
	v_sub_f32_e32 v48, v48, v131
	v_sub_f32_e32 v49, v49, v131
	v_sub_f32_e32 v50, v50, v131
	v_sub_f32_e32 v51, v51, v131
	v_sub_f32_e32 v52, v52, v131
	v_sub_f32_e32 v53, v53, v131
	v_sub_f32_e32 v54, v54, v131
	v_sub_f32_e32 v55, v55, v131
	v_sub_f32_e32 v56, v56, v131
	v_sub_f32_e32 v57, v57, v131
	v_sub_f32_e32 v58, v58, v131
	v_sub_f32_e32 v59, v59, v131
	v_sub_f32_e32 v60, v60, v131
	v_sub_f32_e32 v61, v61, v131
	v_sub_f32_e32 v62, v62, v131
	v_sub_f32_e32 v63, v63, v131
	s_waitcnt lgkmcnt(0)
	v_add_u32_e32 v147, s96, v143
	ds_read_b128 v[2:5], v147
	ds_read_b128 v[6:9], v147 offset:32
	ds_read_b128 v[10:13], v147 offset:64
	ds_read_b128 v[120:123], v147 offset:96
	s_waitcnt lgkmcnt(0)
	v_mul_f32_e32 v16, v16, v2
	v_mul_f32_e32 v32, v32, v2
	v_mul_f32_e32 v17, v17, v3
	v_mul_f32_e32 v33, v33, v3
	v_mul_f32_e32 v18, v18, v4
	v_mul_f32_e32 v34, v34, v4
	v_mul_f32_e32 v19, v19, v5
	v_mul_f32_e32 v35, v35, v5
	v_mul_f32_e32 v20, v20, v6
	v_mul_f32_e32 v36, v36, v6
	v_mul_f32_e32 v21, v21, v7
	v_mul_f32_e32 v37, v37, v7
	v_mul_f32_e32 v22, v22, v8
	v_mul_f32_e32 v38, v38, v8
	v_mul_f32_e32 v23, v23, v9
	v_mul_f32_e32 v39, v39, v9
	v_mul_f32_e32 v24, v24, v10
	v_mul_f32_e32 v40, v40, v10
	v_mul_f32_e32 v25, v25, v11
	v_mul_f32_e32 v41, v41, v11
	v_mul_f32_e32 v26, v26, v12
	v_mul_f32_e32 v42, v42, v12
	v_mul_f32_e32 v27, v27, v13
	v_mul_f32_e32 v43, v43, v13
	v_mul_f32_e32 v28, v28, v120
	v_mul_f32_e32 v44, v44, v120
	v_mul_f32_e32 v29, v29, v121
	v_mul_f32_e32 v45, v45, v121
	v_mul_f32_e32 v30, v30, v122
	v_mul_f32_e32 v46, v46, v122
	v_mul_f32_e32 v31, v31, v123
	v_mul_f32_e32 v47, v47, v123
	s_branch .Lat_u1y_back
.Lat_u1x_noqk:
	s_lshr_b32 s4, s69, 1
	s_sub_u32 s4, s52, s4
	s_sub_u32 s4, s4, 1
	s_cmp_gt_i32 s4, s87
	s_cbranch_scc1 .Lat_u1x_idle
	s_lshl_b32 s4, s50, 13
	s_add_i32 s4, s4, 0x6000
	s_and_b32 s4, s4, 0x6000
	v_add_u32_e32 v159, s4, v144
	ds_read_b64_tr_b16 v[196:197], v159 offset:36864
	ds_read_b64_tr_b16 v[198:199], v159 offset:37376
	ds_read_b64_tr_b16 v[200:201], v159 offset:37888
	ds_read_b64_tr_b16 v[202:203], v159 offset:38400
	ds_read_b64_tr_b16 v[204:205], v159 offset:38912
	ds_read_b64_tr_b16 v[206:207], v159 offset:39424
	ds_read_b64_tr_b16 v[208:209], v159 offset:39936
	ds_read_b64_tr_b16 v[210:211], v159 offset:40448
	ds_read_b64_tr_b16 v[212:213], v159 offset:40960
	ds_read_b64_tr_b16 v[214:215], v159 offset:41472
	ds_read_b64_tr_b16 v[230:231], v159 offset:41984
	ds_read_b64_tr_b16 v[232:233], v159 offset:42496
	ds_read_b64_tr_b16 v[234:235], v159 offset:43008
	ds_read_b64_tr_b16 v[236:237], v159 offset:43520
	ds_read_b64_tr_b16 v[164:165], v159 offset:44032
	ds_read_b64_tr_b16 v[166:167], v159 offset:44544
	v_mov_b32_e32 v156, 0
	v_mov_b32_e32 v157, 0
	v_exp_f32_e32 v64, v64
	v_exp_f32_e32 v65, v65
	v_add_f32_e32 v156, v156, v64
	v_add_f32_e32 v156, v156, v65
	v_cvt_pk_bf16_f32 v64, v64, v65
	v_exp_f32_e32 v66, v66
	v_exp_f32_e32 v67, v67
	v_add_f32_e32 v157, v157, v66
	v_add_f32_e32 v157, v157, v67
	v_cvt_pk_bf16_f32 v65, v66, v67
	v_exp_f32_e32 v68, v68
	v_exp_f32_e32 v69, v69
	v_add_f32_e32 v156, v156, v68
	v_add_f32_e32 v156, v156, v69
	v_cvt_pk_bf16_f32 v66, v68, v69
	v_exp_f32_e32 v70, v70
	v_exp_f32_e32 v71, v71
	v_add_f32_e32 v157, v157, v70
	v_add_f32_e32 v157, v157, v71
	v_cvt_pk_bf16_f32 v67, v70, v71
	v_exp_f32_e32 v72, v72
	v_exp_f32_e32 v73, v73
	v_add_f32_e32 v156, v156, v72
	v_add_f32_e32 v156, v156, v73
	v_cvt_pk_bf16_f32 v68, v72, v73
	v_exp_f32_e32 v74, v74
	v_exp_f32_e32 v75, v75
	v_add_f32_e32 v157, v157, v74
	v_add_f32_e32 v157, v157, v75
	v_cvt_pk_bf16_f32 v69, v74, v75
	v_exp_f32_e32 v76, v76
	v_exp_f32_e32 v77, v77
	v_add_f32_e32 v156, v156, v76
	v_add_f32_e32 v156, v156, v77
	v_cvt_pk_bf16_f32 v70, v76, v77
	v_exp_f32_e32 v78, v78
	v_exp_f32_e32 v79, v79
	v_add_f32_e32 v157, v157, v78
	v_add_f32_e32 v157, v157, v79
	v_cvt_pk_bf16_f32 v71, v78, v79
	s_nop 1
	s_waitcnt lgkmcnt(0)
	v_mfma_f32_32x32x16_bf16 v[16:31], v[64:67], v[196:199], v[16:31]
	v_exp_f32_e32 v48, v48
	v_exp_f32_e32 v49, v49
	v_add_f32_e32 v156, v156, v48
	v_add_f32_e32 v156, v156, v49
	v_cvt_pk_bf16_f32 v48, v48, v49
	v_exp_f32_e32 v50, v50
	v_exp_f32_e32 v51, v51
	v_add_f32_e32 v157, v157, v50
	v_add_f32_e32 v157, v157, v51
	v_cvt_pk_bf16_f32 v49, v50, v51
	v_mfma_f32_32x32x16_bf16 v[32:47], v[64:67], v[212:215], v[32:47]
	v_exp_f32_e32 v52, v52
	v_exp_f32_e32 v53, v53
	v_add_f32_e32 v156, v156, v52
	v_add_f32_e32 v156, v156, v53
	v_cvt_pk_bf16_f32 v50, v52, v53
	v_exp_f32_e32 v54, v54
	v_exp_f32_e32 v55, v55
	v_add_f32_e32 v157, v157, v54
	v_add_f32_e32 v157, v157, v55
	v_cvt_pk_bf16_f32 v51, v54, v55
	v_mfma_f32_32x32x16_bf16 v[16:31], v[68:71], v[200:203], v[16:31]
	v_exp_f32_e32 v56, v56
	v_exp_f32_e32 v57, v57
	v_add_f32_e32 v156, v156, v56
	v_add_f32_e32 v156, v156, v57
	v_cvt_pk_bf16_f32 v52, v56, v57
	v_exp_f32_e32 v58, v58
	v_exp_f32_e32 v59, v59
	v_add_f32_e32 v157, v157, v58
	v_add_f32_e32 v157, v157, v59
	v_cvt_pk_bf16_f32 v53, v58, v59
	v_mfma_f32_32x32x16_bf16 v[32:47], v[68:71], v[230:233], v[32:47]
	v_exp_f32_e32 v60, v60
	v_exp_f32_e32 v61, v61
	v_add_f32_e32 v156, v156, v60
	v_add_f32_e32 v156, v156, v61
	v_cvt_pk_bf16_f32 v54, v60, v61
	v_exp_f32_e32 v62, v62
	v_exp_f32_e32 v63, v63
	v_add_f32_e32 v157, v157, v62
	v_add_f32_e32 v157, v157, v63
	v_cvt_pk_bf16_f32 v55, v62, v63
	s_nop 1
	v_mfma_f32_32x32x16_bf16 v[16:31], v[48:51], v[204:207], v[16:31]
	v_mfma_f32_32x32x16_bf16 v[32:47], v[48:51], v[234:237], v[32:47]
	v_mfma_f32_32x32x16_bf16 v[16:31], v[52:55], v[208:211], v[16:31]
	v_mfma_f32_32x32x16_bf16 v[32:47], v[52:55], v[164:167], v[32:47]
	v_add_f32_e32 v156, v156, v157
	v_add_f32_e32 v128, v128, v156
.Lat_u1x_idle:
	s_mul_i32 s53, s48, 0x3000
	s_add_i32 s4, s52, 2
	s_cmp_ge_u32 s4, s86
	s_cbranch_scc1 .Lat_u1xn_nodma
	s_add_i32 s4, s53, 0xffffd000
	s_cmp_lg_u32 s48, 0
	s_cselect_b32 s4, s4, 0x6000
	s_add_i32 s5, s4, s97
	s_mov_b32 m0, s5
	s_add_i32 s4, s4, s72
	global_load_lds_dwordx4 v[126:127], off
	s_mov_b32 m0, s4
	s_lshl_b32 s5, s50, 13
	global_load_lds_dwordx4 v[14:15], off
	s_xor_b32 s5, s5, 0x4000
	s_add_i32 s5, s5, s73
	s_mov_b32 m0, s5
	s_nop 0
	global_load_lds_dwordx4 v[124:125], off
; __device__ __forceinline__ void attn_unit(int b, int h, int qb, const bf16* Q, const bf16* __restrict__ Kn, const bf16* __restrict__ Kpe, const bf16* __restrict__ V, bf16* O, float* ASS, LAS char* shm) {
;     ...
;             ks = (ks == 2) ? 0 : ks + 1; vs = (vs + 1) & 3;
.Lat_u1xn_nodma:
	v_lshl_add_u64 v[126:127], v[126:127], 0, s[34:35]
	v_lshl_add_u64 v[14:15], v[14:15], 0, s[20:21]
	v_lshl_add_u64 v[124:125], v[124:125], 0, s[34:35]
	s_add_i32 s52, s52, 1
	s_add_i32 s4, s48, 1
	s_cmp_lg_u32 s48, 2
	s_cselect_b32 s48, s4, 0
	s_add_i32 s50, s50, 1
	s_and_b32 s50, s50, 3
	s_branch .Lat_u1x_end
.Lat_u1y_noqk:
	s_lshr_b32 s4, s69, 1
	s_sub_u32 s4, s52, s4
	s_sub_u32 s4, s4, 1
	s_cmp_gt_i32 s4, s87
	s_cbranch_scc1 .Lat_u1y_idle
	s_lshl_b32 s4, s50, 13
	s_add_i32 s4, s4, 0x6000
	s_and_b32 s4, s4, 0x6000
	v_add_u32_e32 v159, s4, v144
	ds_read_b64_tr_b16 v[196:197], v159 offset:36864
	ds_read_b64_tr_b16 v[198:199], v159 offset:37376
	ds_read_b64_tr_b16 v[200:201], v159 offset:37888
	ds_read_b64_tr_b16 v[202:203], v159 offset:38400
	ds_read_b64_tr_b16 v[204:205], v159 offset:38912
	ds_read_b64_tr_b16 v[206:207], v159 offset:39424
	ds_read_b64_tr_b16 v[208:209], v159 offset:39936
	ds_read_b64_tr_b16 v[210:211], v159 offset:40448
	ds_read_b64_tr_b16 v[212:213], v159 offset:40960
	ds_read_b64_tr_b16 v[214:215], v159 offset:41472
	ds_read_b64_tr_b16 v[230:231], v159 offset:41984
	ds_read_b64_tr_b16 v[232:233], v159 offset:42496
	ds_read_b64_tr_b16 v[234:235], v159 offset:43008
	ds_read_b64_tr_b16 v[236:237], v159 offset:43520
	ds_read_b64_tr_b16 v[164:165], v159 offset:44032
	ds_read_b64_tr_b16 v[166:167], v159 offset:44544
	v_mov_b32_e32 v156, 0
	v_mov_b32_e32 v157, 0
	v_exp_f32_e32 v238, v238
	v_exp_f32_e32 v239, v239
	v_add_f32_e32 v156, v156, v238
	v_add_f32_e32 v156, v156, v239
	v_cvt_pk_bf16_f32 v238, v238, v239
	v_exp_f32_e32 v240, v240
	v_exp_f32_e32 v241, v241
	v_add_f32_e32 v157, v157, v240
	v_add_f32_e32 v157, v157, v241
	v_cvt_pk_bf16_f32 v239, v240, v241
	v_exp_f32_e32 v242, v242
	v_exp_f32_e32 v243, v243
	v_add_f32_e32 v156, v156, v242
	v_add_f32_e32 v156, v156, v243
	v_cvt_pk_bf16_f32 v240, v242, v243
	v_exp_f32_e32 v244, v244
	v_exp_f32_e32 v245, v245
	v_add_f32_e32 v157, v157, v244
	v_add_f32_e32 v157, v157, v245
	v_cvt_pk_bf16_f32 v241, v244, v245
	v_exp_f32_e32 v246, v246
	v_exp_f32_e32 v247, v247
	v_add_f32_e32 v156, v156, v246
	v_add_f32_e32 v156, v156, v247
	v_cvt_pk_bf16_f32 v242, v246, v247
	v_exp_f32_e32 v248, v248
	v_exp_f32_e32 v249, v249
	v_add_f32_e32 v157, v157, v248
	v_add_f32_e32 v157, v157, v249
	v_cvt_pk_bf16_f32 v243, v248, v249
	v_exp_f32_e32 v250, v250
	v_exp_f32_e32 v251, v251
	v_add_f32_e32 v156, v156, v250
	v_add_f32_e32 v156, v156, v251
	v_cvt_pk_bf16_f32 v244, v250, v251
	v_exp_f32_e32 v252, v252
	v_exp_f32_e32 v253, v253
	v_add_f32_e32 v157, v157, v252
	v_add_f32_e32 v157, v157, v253
	v_cvt_pk_bf16_f32 v245, v252, v253
	s_nop 1
	s_waitcnt lgkmcnt(0)
	v_mfma_f32_32x32x16_bf16 v[16:31], v[238:241], v[196:199], v[16:31]
	v_exp_f32_e32 v180, v180
	v_exp_f32_e32 v181, v181
	v_add_f32_e32 v156, v156, v180
	v_add_f32_e32 v156, v156, v181
	v_cvt_pk_bf16_f32 v180, v180, v181
	v_exp_f32_e32 v182, v182
	v_exp_f32_e32 v183, v183
	v_add_f32_e32 v157, v157, v182
	v_add_f32_e32 v157, v157, v183
	v_cvt_pk_bf16_f32 v181, v182, v183
	v_mfma_f32_32x32x16_bf16 v[32:47], v[238:241], v[212:215], v[32:47]
	v_exp_f32_e32 v184, v184
	v_exp_f32_e32 v185, v185
	v_add_f32_e32 v156, v156, v184
	v_add_f32_e32 v156, v156, v185
	v_cvt_pk_bf16_f32 v182, v184, v185
	v_exp_f32_e32 v186, v186
	v_exp_f32_e32 v187, v187
	v_add_f32_e32 v157, v157, v186
	v_add_f32_e32 v157, v157, v187
	v_cvt_pk_bf16_f32 v183, v186, v187
	v_mfma_f32_32x32x16_bf16 v[16:31], v[242:245], v[200:203], v[16:31]
	v_exp_f32_e32 v188, v188
	v_exp_f32_e32 v189, v189
	v_add_f32_e32 v156, v156, v188
	v_add_f32_e32 v156, v156, v189
	v_cvt_pk_bf16_f32 v184, v188, v189
	v_exp_f32_e32 v190, v190
	v_exp_f32_e32 v191, v191
	v_add_f32_e32 v157, v157, v190
	v_add_f32_e32 v157, v157, v191
	v_cvt_pk_bf16_f32 v185, v190, v191
	v_mfma_f32_32x32x16_bf16 v[32:47], v[242:245], v[230:233], v[32:47]
	v_exp_f32_e32 v192, v192
	v_exp_f32_e32 v193, v193
	v_add_f32_e32 v156, v156, v192
	v_add_f32_e32 v156, v156, v193
	v_cvt_pk_bf16_f32 v186, v192, v193
	v_exp_f32_e32 v194, v194
	v_exp_f32_e32 v195, v195
	v_add_f32_e32 v157, v157, v194
	v_add_f32_e32 v157, v157, v195
	v_cvt_pk_bf16_f32 v187, v194, v195
	s_nop 1
	v_mfma_f32_32x32x16_bf16 v[16:31], v[180:183], v[204:207], v[16:31]
	v_mfma_f32_32x32x16_bf16 v[32:47], v[180:183], v[234:237], v[32:47]
	v_mfma_f32_32x32x16_bf16 v[16:31], v[184:187], v[208:211], v[16:31]
	v_mfma_f32_32x32x16_bf16 v[32:47], v[184:187], v[164:167], v[32:47]
	v_add_f32_e32 v156, v156, v157
	v_add_f32_e32 v128, v128, v156

; #define SBAR() __builtin_amdgcn_sched_barrier(0)
; #define WAIT_BAR(N) asm volatile("s_waitcnt vmcnt(" #N ") lgkmcnt(0)\n\ts_barrier" ::: "memory")
; #define DMA_TILE(t, ks, vs) do { glds16(ksrc + (long)(t) * KVBLK * KNP, (unsigned)__builtin_amdgcn_readfirstlane(kdst + (ks) * KSLOT)); \
;         glds16(k2src + (long)(t) * KVBLK * KPP, (unsigned)__builtin_amdgcn_readfirstlane(k2dst + (ks) * KSLOT)); \
;         glds16(vsrc + (long)(t) * KVBLK * VP, (unsigned)__builtin_amdgcn_readfirstlane(vdst + (vs) * VSLOT)); } while (0)
; #define K_LOAD(ks) do { const LAS char* kp_ = kp0 + (ks) * KSLOT; \
;         _Pragma("unroll") for (int i_ = 0; i_ < 6; ++i_) { kf[2 * i_] = *(const LAS bf16x8*)(kp_ + i_ * 2048); kf[2 * i_ + 1] = *(const LAS bf16x8*)(kp_ + i_ * 2048 + 512); } SBAR(); } while (0)
; #define V_LOAD(vs) do { const LAS char* vp_ = vp0 + (vs) * VSLOT; \
;         _Pragma("unroll") for (int i_ = 0; i_ < 8; ++i_) { vlo[i_] = vtr(vp_ + ((i_ >> 2) * 4096 + (i_ & 3) * 1024)); vhi[i_] = vtr(vp_ + ((i_ >> 2) * 4096 + (i_ & 3) * 1024 + 512)); } SBAR(); } while (0)
; __device__ __forceinline__ void attn_unit(int b, int h, int qb, const bf16* Q, const bf16* __restrict__ Kn, const bf16* __restrict__ Kpe, const bf16* __restrict__ V, bf16* O, float* ASS, LAS char* shm) {
;     ...
;         for (int t = 0; t < NT; ++t) {
;             if (t + 1 < NT) { WAIT_BAR(3); } else { WAIT_BAR(0); }
;             if (t > 0) V_LOAD((vs + 3) & 3);
;             if (t + 2 < NT) DMA_TILE(t + 2, (ks == 0) ? 2 : ks - 1, (vs + 2) & 3);
;             SBAR();
;             if (t > 0) SOFTMAX();
;             K_LOAD(ks);
;             if (t > 0) PV_MMA();
;             QK_MMA(t);
.Lat_u2x_bar:
	s_barrier
	s_lshr_b32 s4, s56, 1
	s_sub_u32 s4, s62, s4
	s_cmp_gt_i32 s4, s91
	s_cbranch_scc1 .Lat_u2x_noqk
	s_mul_i32 s63, s61, 0x3000
	v_add_u32_e32 v158, s63, v146
	ds_read_b128 v[196:199], v158
	ds_read_b128 v[200:203], v158 offset:512
	ds_read_b128 v[204:207], v158 offset:2048
	ds_read_b128 v[208:211], v158 offset:2560
	ds_read_b128 v[212:215], v158 offset:4096
	ds_read_b128 v[230:233], v158 offset:4608
	ds_read_b128 v[234:237], v158 offset:6144
	ds_read_b128 v[164:167], v158 offset:6656
	ds_read_b128 v[168:171], v158 offset:8192
	ds_read_b128 v[172:175], v158 offset:8704
	ds_read_b128 v[148:151], v158 offset:10240
	ds_read_b128 v[152:155], v158 offset:10752
	s_lshl_b32 s4, s64, 13
	s_add_i32 s4, s4, 0x6000
	s_and_b32 s4, s4, 0x6000
	v_add_u32_e32 v159, s4, v143
	v_mov_b32_e32 v156, 0
	v_mov_b32_e32 v157, 0
	s_waitcnt lgkmcnt(11)
	v_mfma_f32_32x32x16_bf16 v[238:253], v[196:199], v[86:89], v[104:119]
	ds_read_b64_tr_b16 v[196:197], v159 offset:36864
	ds_read_b64_tr_b16 v[198:199], v159 offset:37376
	v_exp_f32_e32 v50, v50
	v_exp_f32_e32 v51, v51
	v_add_f32_e32 v156, v156, v50
	v_add_f32_e32 v156, v156, v51
	v_cvt_pk_bf16_f32 v50, v50, v51
	s_waitcnt lgkmcnt(12)
	v_mfma_f32_32x32x16_bf16 v[180:195], v[200:203], v[86:89], v[104:119]
	ds_read_b64_tr_b16 v[200:201], v159 offset:37888
	ds_read_b64_tr_b16 v[202:203], v159 offset:38400
	v_exp_f32_e32 v52, v52
	v_exp_f32_e32 v53, v53
	v_add_f32_e32 v157, v157, v52
	v_add_f32_e32 v157, v157, v53
	v_cvt_pk_bf16_f32 v51, v52, v53
	s_waitcnt lgkmcnt(13)
	v_mfma_f32_32x32x16_bf16 v[238:253], v[204:207], v[82:85], v[238:253]
	ds_read_b64_tr_b16 v[204:205], v159 offset:38912
	ds_read_b64_tr_b16 v[206:207], v159 offset:39424
	v_exp_f32_e32 v54, v54
	v_exp_f32_e32 v55, v55
	v_add_f32_e32 v156, v156, v54
	v_add_f32_e32 v156, v156, v55
	v_cvt_pk_bf16_f32 v52, v54, v55
	s_waitcnt lgkmcnt(14)
	v_mfma_f32_32x32x16_bf16 v[180:195], v[208:211], v[82:85], v[180:195]
	ds_read_b64_tr_b16 v[208:209], v159 offset:39936
	ds_read_b64_tr_b16 v[210:211], v159 offset:40448
	v_exp_f32_e32 v56, v56
	v_exp_f32_e32 v57, v57
	v_add_f32_e32 v157, v157, v56
	v_add_f32_e32 v157, v157, v57
	v_cvt_pk_bf16_f32 v53, v56, v57
	s_waitcnt lgkmcnt(15)
	v_mfma_f32_32x32x16_bf16 v[238:253], v[212:215], v[78:81], v[238:253]
	ds_read_b64_tr_b16 v[212:213], v159 offset:40960
	ds_read_b64_tr_b16 v[214:215], v159 offset:41472
	v_exp_f32_e32 v58, v58
	v_exp_f32_e32 v59, v59
	v_add_f32_e32 v156, v156, v58
	v_add_f32_e32 v156, v156, v59
	v_cvt_pk_bf16_f32 v54, v58, v59
	s_waitcnt lgkmcnt(15)
	v_mfma_f32_32x32x16_bf16 v[180:195], v[230:233], v[78:81], v[180:195]
	ds_read_b64_tr_b16 v[230:231], v159 offset:41984
	ds_read_b64_tr_b16 v[232:233], v159 offset:42496
	v_exp_f32_e32 v60, v60
	v_exp_f32_e32 v61, v61
	v_add_f32_e32 v157, v157, v60
	v_add_f32_e32 v157, v157, v61
	v_cvt_pk_bf16_f32 v55, v60, v61
	s_waitcnt lgkmcnt(15)
	v_mfma_f32_32x32x16_bf16 v[238:253], v[234:237], v[74:77], v[238:253]
	ds_read_b64_tr_b16 v[234:235], v159 offset:43008
	ds_read_b64_tr_b16 v[236:237], v159 offset:43520
	v_exp_f32_e32 v62, v62
	v_exp_f32_e32 v63, v63
	v_add_f32_e32 v156, v156, v62
	v_add_f32_e32 v156, v156, v63
	v_cvt_pk_bf16_f32 v56, v62, v63
	s_waitcnt lgkmcnt(15)
	v_mfma_f32_32x32x16_bf16 v[180:195], v[164:167], v[74:77], v[180:195]
	ds_read_b64_tr_b16 v[164:165], v159 offset:44032
	ds_read_b64_tr_b16 v[166:167], v159 offset:44544
	v_exp_f32_e32 v64, v64
	v_exp_f32_e32 v65, v65
	v_add_f32_e32 v157, v157, v64
	v_add_f32_e32 v157, v157, v65
	v_cvt_pk_bf16_f32 v57, v64, v65
	s_waitcnt lgkmcnt(15)
	v_mfma_f32_32x32x16_bf16 v[238:253], v[168:171], v[70:73], v[238:253]
	v_exp_f32_e32 v34, v34
	v_exp_f32_e32 v35, v35
	v_add_f32_e32 v156, v156, v34
	v_add_f32_e32 v156, v156, v35
	v_cvt_pk_bf16_f32 v34, v34, v35
	s_waitcnt lgkmcnt(15)
	v_mfma_f32_32x32x16_bf16 v[180:195], v[172:175], v[70:73], v[180:195]
	v_exp_f32_e32 v36, v36
	v_exp_f32_e32 v37, v37
	v_add_f32_e32 v157, v157, v36
	v_add_f32_e32 v157, v157, v37
	v_cvt_pk_bf16_f32 v35, v36, v37
	s_waitcnt lgkmcnt(15)
	v_mfma_f32_32x32x16_bf16 v[238:253], v[148:151], v[66:69], v[238:253]
	v_exp_f32_e32 v38, v38
	v_exp_f32_e32 v39, v39
	v_add_f32_e32 v156, v156, v38
	v_add_f32_e32 v156, v156, v39
	v_cvt_pk_bf16_f32 v36, v38, v39
	s_waitcnt lgkmcnt(15)
	v_mfma_f32_32x32x16_bf16 v[180:195], v[152:155], v[66:69], v[180:195]
	v_exp_f32_e32 v40, v40
	v_exp_f32_e32 v41, v41
	v_add_f32_e32 v157, v157, v40
	v_add_f32_e32 v157, v157, v41
	v_cvt_pk_bf16_f32 v37, v40, v41
	s_nop 1
	s_waitcnt lgkmcnt(0)
	v_mfma_f32_32x32x16_bf16 v[18:33], v[50:53], v[196:199], v[18:33]
	v_exp_f32_e32 v42, v42
	v_exp_f32_e32 v43, v43
	v_add_f32_e32 v156, v156, v42
	v_add_f32_e32 v156, v156, v43
	v_cvt_pk_bf16_f32 v38, v42, v43
	s_nop 1
	v_mfma_f32_32x32x16_bf16 v[2:17], v[50:53], v[212:215], v[2:17]
	s_mul_i32 s63, s61, 0x3000
	s_add_i32 s4, s62, 2
	s_cmp_ge_u32 s4, s90
	s_cbranch_scc1 .Lat_u2x_nodma
	s_add_i32 s4, s63, 0xffffd000
	s_cmp_lg_u32 s61, 0
	s_cselect_b32 s4, s4, 0x6000
	s_add_i32 s5, s4, s58
	s_mov_b32 m0, s5
	s_add_i32 s4, s4, s59
	global_load_lds_dwordx4 v[126:127], off
	s_mov_b32 m0, s4
	s_lshl_b32 s5, s64, 13
	global_load_lds_dwordx4 v[122:123], off
	s_xor_b32 s5, s5, 0x4000
	s_add_i32 s5, s5, s60
	s_mov_b32 m0, s5
	s_nop 0
	global_load_lds_dwordx4 v[124:125], off
; __device__ __forceinline__ void cmask(f32x16& p0, f32x16& p1, int jb, int qrel, int hi) {
;     const float NEG = -INFINITY; const int kb = 64 * jb + 4 * hi;
; #pragma unroll
;     for (int r = 0; r < 16; ++r) { const int kv = kb + (r & 3) + 8 * (r >> 2); if (kv > qrel) p0[r] = NEG; if (kv + 32 > qrel) p1[r] = NEG; }
; }
; __device__ __forceinline__ void glds16(const void* gsrc, unsigned lds_dst) { unsigned keep;
;     asm volatile("s_mov_b32 %0, m0\n\ts_mov_b32 m0, %2\n\ts_nop 0\n\tglobal_load_lds_dwordx4 %1, off\n\ts_mov_b32 m0, %0" : "=&s"(keep) : "v"(gsrc), "s"(lds_dst) : "memory"); }
; __device__ __forceinline__ float max3f(float a, float b, float c) { return __builtin_fmaxf(__builtin_fmaxf(a, b), c); }
; __device__ __forceinline__ float rowmax(const f32x16& p0, const f32x16& p1) {
;     float a = max3f(p0[0], p0[1], p1[0]), b = max3f(p0[2], p0[3], p1[1]); a = max3f(a, p1[2], p1[3]);
; #pragma unroll
;     for (int r = 4; r < 16; r += 4) { a = max3f(a, p0[r], p0[r + 1]); b = max3f(b, p0[r + 2], p0[r + 3]); a = max3f(a, p1[r], p1[r + 1]); b = max3f(b, p1[r + 2], p1[r + 3]); }
;     const float m = __builtin_fmaxf(a, b);
;     auto rr = __builtin_amdgcn_permlane32_swap(__float_as_uint(m), __float_as_uint(m), false, false);
;     return __builtin_fmaxf(__uint_as_float(rr[0]), __uint_as_float(rr[1]));
; }
.Lat_u2x_nodma:
	v_lshl_add_u64 v[126:127], v[126:127], 0, s[34:35]
	v_lshl_add_u64 v[122:123], v[122:123], 0, s[20:21]
	v_lshl_add_u64 v[124:125], v[124:125], 0, s[34:35]
	v_exp_f32_e32 v44, v44
	v_exp_f32_e32 v45, v45
	v_add_f32_e32 v157, v157, v44
	v_add_f32_e32 v157, v157, v45
	v_cvt_pk_bf16_f32 v39, v44, v45
	s_nop 1
	v_mfma_f32_32x32x16_bf16 v[18:33], v[54:57], v[200:203], v[18:33]
	v_exp_f32_e32 v46, v46
	v_exp_f32_e32 v47, v47
	v_add_f32_e32 v156, v156, v46
	v_add_f32_e32 v156, v156, v47
	v_cvt_pk_bf16_f32 v40, v46, v47
	s_nop 1
	v_mfma_f32_32x32x16_bf16 v[2:17], v[54:57], v[230:233], v[2:17]
	v_exp_f32_e32 v48, v48
	v_exp_f32_e32 v49, v49
	v_add_f32_e32 v157, v157, v48
	v_add_f32_e32 v157, v157, v49
	v_cvt_pk_bf16_f32 v41, v48, v49
	s_nop 1
	v_mfma_f32_32x32x16_bf16 v[18:33], v[34:37], v[204:207], v[18:33]
	v_mfma_f32_32x32x16_bf16 v[2:17], v[34:37], v[234:237], v[2:17]
	v_mfma_f32_32x32x16_bf16 v[18:33], v[38:41], v[208:211], v[18:33]
	v_mfma_f32_32x32x16_bf16 v[2:17], v[38:41], v[164:167], v[2:17]
	v_add_f32_e32 v156, v156, v157
	v_add_f32_e32 v128, v128, v156
	s_cmp_lt_u32 s62, s91
	s_cbranch_scc1 .Lat_u2x_nomask
	s_sub_i32 s4, s62, s91
	s_lshl_b32 s4, s4, 6
	s_nop 7
	s_nop 7
	v_lshl_add_u32 v133, v142, 2, s4
	v_sub_u32_e32 v133, v145, v133
	v_cmp_gt_i32_e32 vcc, 0, v133
	s_nop 1
	v_cndmask_b32_e32 v238, v238, v220, vcc
	v_cmp_gt_i32_e32 vcc, 1, v133
	s_nop 1
	v_cndmask_b32_e32 v239, v239, v220, vcc
	v_cmp_gt_i32_e32 vcc, 2, v133
	s_nop 1
	v_cndmask_b32_e32 v240, v240, v220, vcc
	v_cmp_gt_i32_e32 vcc, 3, v133
	s_nop 1
	v_cndmask_b32_e32 v241, v241, v220, vcc
	v_cmp_gt_i32_e32 vcc, 8, v133
	s_nop 1
	v_cndmask_b32_e32 v242, v242, v220, vcc
	v_cmp_gt_i32_e32 vcc, 9, v133
	s_nop 1
	v_cndmask_b32_e32 v243, v243, v220, vcc
	v_cmp_gt_i32_e32 vcc, 10, v133
	s_nop 1
	v_cndmask_b32_e32 v244, v244, v220, vcc
	v_cmp_gt_i32_e32 vcc, 11, v133
	s_nop 1
	v_cndmask_b32_e32 v245, v245, v220, vcc
	v_cmp_gt_i32_e32 vcc, 16, v133
	s_nop 1
	v_cndmask_b32_e32 v246, v246, v220, vcc
	v_cmp_gt_i32_e32 vcc, 17, v133
	s_nop 1
	v_cndmask_b32_e32 v247, v247, v220, vcc
	v_cmp_gt_i32_e32 vcc, 18, v133
	s_nop 1
	v_cndmask_b32_e32 v248, v248, v220, vcc
	v_cmp_gt_i32_e32 vcc, 19, v133
	s_nop 1
	v_cndmask_b32_e32 v249, v249, v220, vcc
	v_cmp_gt_i32_e32 vcc, 24, v133
	s_nop 1
	v_cndmask_b32_e32 v250, v250, v220, vcc
	v_cmp_gt_i32_e32 vcc, 25, v133
	s_nop 1
	v_cndmask_b32_e32 v251, v251, v220, vcc
	v_cmp_gt_i32_e32 vcc, 26, v133
	s_nop 1
	v_cndmask_b32_e32 v252, v252, v220, vcc
	v_cmp_gt_i32_e32 vcc, 27, v133
	s_nop 1
	v_cndmask_b32_e32 v253, v253, v220, vcc
	v_cmp_gt_i32_e32 vcc, 32, v133
	s_nop 1
	v_cndmask_b32_e32 v180, v180, v220, vcc
	v_cmp_gt_i32_e32 vcc, 33, v133
	s_nop 1
	v_cndmask_b32_e32 v181, v181, v220, vcc
	v_cmp_gt_i32_e32 vcc, 34, v133
	s_nop 1
	v_cndmask_b32_e32 v182, v182, v220, vcc
	v_cmp_gt_i32_e32 vcc, 35, v133
	s_nop 1
	v_cndmask_b32_e32 v183, v183, v220, vcc
	v_cmp_gt_i32_e32 vcc, 40, v133
	s_nop 1
	v_cndmask_b32_e32 v184, v184, v220, vcc
	v_cmp_gt_i32_e32 vcc, 41, v133
	s_nop 1
	v_cndmask_b32_e32 v185, v185, v220, vcc
	v_cmp_gt_i32_e32 vcc, 42, v133
	s_nop 1
	v_cndmask_b32_e32 v186, v186, v220, vcc
	v_cmp_gt_i32_e32 vcc, 43, v133
	s_nop 1
	v_cndmask_b32_e32 v187, v187, v220, vcc
	v_cmp_gt_i32_e32 vcc, 48, v133
	s_nop 1
	v_cndmask_b32_e32 v188, v188, v220, vcc
	v_cmp_gt_i32_e32 vcc, 49, v133
	s_nop 1
	v_cndmask_b32_e32 v189, v189, v220, vcc
	v_cmp_gt_i32_e32 vcc, 50, v133
	s_nop 1
	v_cndmask_b32_e32 v190, v190, v220, vcc
	v_cmp_gt_i32_e32 vcc, 51, v133
	s_nop 1
	v_cndmask_b32_e32 v191, v191, v220, vcc
	v_cmp_gt_i32_e32 vcc, 56, v133
	s_nop 1
	v_cndmask_b32_e32 v192, v192, v220, vcc
	v_cmp_gt_i32_e32 vcc, 57, v133
	s_nop 1
	v_cndmask_b32_e32 v193, v193, v220, vcc
	v_cmp_gt_i32_e32 vcc, 58, v133
	s_nop 1
	v_cndmask_b32_e32 v194, v194, v220, vcc
	v_cmp_gt_i32_e32 vcc, 59, v133
	s_nop 1
	v_cndmask_b32_e32 v195, v195, v220, vcc
.Lat_u2x_nomask:
	v_max3_f32 v131, v238, v239, v240
	v_max3_f32 v132, v241, v242, v243
	v_max3_f32 v131, v131, v244, v245
	v_max3_f32 v132, v132, v246, v247
	v_max3_f32 v131, v131, v248, v249
	v_max3_f32 v132, v132, v250, v251
	v_max3_f32 v131, v131, v252, v253
	v_max3_f32 v132, v132, v180, v181
	v_max3_f32 v131, v131, v182, v183
	v_max3_f32 v132, v132, v184, v185
	v_max3_f32 v131, v131, v186, v187
	v_max3_f32 v132, v132, v188, v189
	v_max3_f32 v131, v131, v190, v191
	v_max3_f32 v132, v132, v192, v193
	v_max3_f32 v131, v131, v194, v195
	v_max_f32_e32 v131, v131, v132
	v_cmp_lt_f32_e32 vcc, 0x41000000, v131
	s_cbranch_vccnz .Lat_u2x_rare

; #define WAIT_BAR(N) asm volatile("s_waitcnt vmcnt(" #N ") lgkmcnt(0)\n\ts_barrier" ::: "memory")
; __device__ __forceinline__ void attn_unit(int b, int h, int qb, const bf16* Q, const bf16* __restrict__ Kn, const bf16* __restrict__ Kpe, const bf16* __restrict__ V, bf16* O, float* ASS, LAS char* shm) {
;     ...
;         for (int t = 0; t < NT; ++t) {
;             if (t + 1 < NT) { WAIT_BAR(3); } else { WAIT_BAR(0); }
.Lat_u2x_end:
	s_cmp_eq_u32 s62, s90
	s_cbranch_scc1 .Lat_u2_tail
	s_add_i32 s4, s62, 1
	s_cmp_ge_u32 s4, s90
	s_cbranch_scc1 .Lat_u2y_lw
	s_waitcnt vmcnt(3) lgkmcnt(0)
	s_branch .Lat_u2y_bar

; #define SBAR() __builtin_amdgcn_sched_barrier(0)
; #define WAIT_BAR(N) asm volatile("s_waitcnt vmcnt(" #N ") lgkmcnt(0)\n\ts_barrier" ::: "memory")
; #define DMA_TILE(t, ks, vs) do { glds16(ksrc + (long)(t) * KVBLK * KNP, (unsigned)__builtin_amdgcn_readfirstlane(kdst + (ks) * KSLOT)); \
;         glds16(k2src + (long)(t) * KVBLK * KPP, (unsigned)__builtin_amdgcn_readfirstlane(k2dst + (ks) * KSLOT)); \
;         glds16(vsrc + (long)(t) * KVBLK * VP, (unsigned)__builtin_amdgcn_readfirstlane(vdst + (vs) * VSLOT)); } while (0)
; #define K_LOAD(ks) do { const LAS char* kp_ = kp0 + (ks) * KSLOT; \
;         _Pragma("unroll") for (int i_ = 0; i_ < 6; ++i_) { kf[2 * i_] = *(const LAS bf16x8*)(kp_ + i_ * 2048); kf[2 * i_ + 1] = *(const LAS bf16x8*)(kp_ + i_ * 2048 + 512); } SBAR(); } while (0)
; #define V_LOAD(vs) do { const LAS char* vp_ = vp0 + (vs) * VSLOT; \
;         _Pragma("unroll") for (int i_ = 0; i_ < 8; ++i_) { vlo[i_] = vtr(vp_ + ((i_ >> 2) * 4096 + (i_ & 3) * 1024)); vhi[i_] = vtr(vp_ + ((i_ >> 2) * 4096 + (i_ & 3) * 1024 + 512)); } SBAR(); } while (0)
; __device__ __forceinline__ void attn_unit(int b, int h, int qb, const bf16* Q, const bf16* __restrict__ Kn, const bf16* __restrict__ Kpe, const bf16* __restrict__ V, bf16* O, float* ASS, LAS char* shm) {
;     ...
;         for (int t = 0; t < NT; ++t) {
;             if (t + 1 < NT) { WAIT_BAR(3); } else { WAIT_BAR(0); }
;             if (t > 0) V_LOAD((vs + 3) & 3);
;             if (t + 2 < NT) DMA_TILE(t + 2, (ks == 0) ? 2 : ks - 1, (vs + 2) & 3);
;             SBAR();
;             if (t > 0) SOFTMAX();
;             K_LOAD(ks);
;             if (t > 0) PV_MMA();
;             QK_MMA(t);
.Lat_u2y_bar:
	s_barrier
	s_lshr_b32 s4, s56, 1
	s_sub_u32 s4, s62, s4
	s_cmp_gt_i32 s4, s91
	s_cbranch_scc1 .Lat_u2y_noqk
	s_mul_i32 s63, s61, 0x3000
	v_add_u32_e32 v158, s63, v146
	ds_read_b128 v[196:199], v158
	ds_read_b128 v[200:203], v158 offset:512
	ds_read_b128 v[204:207], v158 offset:2048
	ds_read_b128 v[208:211], v158 offset:2560
	ds_read_b128 v[212:215], v158 offset:4096
	ds_read_b128 v[230:233], v158 offset:4608
	ds_read_b128 v[234:237], v158 offset:6144
	ds_read_b128 v[164:167], v158 offset:6656
	ds_read_b128 v[168:171], v158 offset:8192
	ds_read_b128 v[172:175], v158 offset:8704
	ds_read_b128 v[148:151], v158 offset:10240
	ds_read_b128 v[152:155], v158 offset:10752
	s_lshl_b32 s4, s64, 13
	s_add_i32 s4, s4, 0x6000
	s_and_b32 s4, s4, 0x6000
	v_add_u32_e32 v159, s4, v143
	v_mov_b32_e32 v156, 0
	v_mov_b32_e32 v157, 0
	s_waitcnt lgkmcnt(11)
	v_mfma_f32_32x32x16_bf16 v[50:65], v[196:199], v[86:89], v[104:119]
	ds_read_b64_tr_b16 v[196:197], v159 offset:36864
	ds_read_b64_tr_b16 v[198:199], v159 offset:37376
	v_exp_f32_e32 v238, v238
	v_exp_f32_e32 v239, v239
	v_add_f32_e32 v156, v156, v238
	v_add_f32_e32 v156, v156, v239
	v_cvt_pk_bf16_f32 v238, v238, v239
	s_waitcnt lgkmcnt(12)
	v_mfma_f32_32x32x16_bf16 v[34:49], v[200:203], v[86:89], v[104:119]
	ds_read_b64_tr_b16 v[200:201], v159 offset:37888
	ds_read_b64_tr_b16 v[202:203], v159 offset:38400
	v_exp_f32_e32 v240, v240
	v_exp_f32_e32 v241, v241
	v_add_f32_e32 v157, v157, v240
	v_add_f32_e32 v157, v157, v241
	v_cvt_pk_bf16_f32 v239, v240, v241
	s_waitcnt lgkmcnt(13)
	v_mfma_f32_32x32x16_bf16 v[50:65], v[204:207], v[82:85], v[50:65]
	ds_read_b64_tr_b16 v[204:205], v159 offset:38912
	ds_read_b64_tr_b16 v[206:207], v159 offset:39424
	v_exp_f32_e32 v242, v242
	v_exp_f32_e32 v243, v243
	v_add_f32_e32 v156, v156, v242
	v_add_f32_e32 v156, v156, v243
	v_cvt_pk_bf16_f32 v240, v242, v243
	s_waitcnt lgkmcnt(14)
	v_mfma_f32_32x32x16_bf16 v[34:49], v[208:211], v[82:85], v[34:49]
	ds_read_b64_tr_b16 v[208:209], v159 offset:39936
	ds_read_b64_tr_b16 v[210:211], v159 offset:40448
	v_exp_f32_e32 v244, v244
	v_exp_f32_e32 v245, v245
	v_add_f32_e32 v157, v157, v244
	v_add_f32_e32 v157, v157, v245
	v_cvt_pk_bf16_f32 v241, v244, v245
	s_waitcnt lgkmcnt(15)
	v_mfma_f32_32x32x16_bf16 v[50:65], v[212:215], v[78:81], v[50:65]
	ds_read_b64_tr_b16 v[212:213], v159 offset:40960
	ds_read_b64_tr_b16 v[214:215], v159 offset:41472
	v_exp_f32_e32 v246, v246
	v_exp_f32_e32 v247, v247
	v_add_f32_e32 v156, v156, v246
	v_add_f32_e32 v156, v156, v247
	v_cvt_pk_bf16_f32 v242, v246, v247
	s_waitcnt lgkmcnt(15)
	v_mfma_f32_32x32x16_bf16 v[34:49], v[230:233], v[78:81], v[34:49]
	ds_read_b64_tr_b16 v[230:231], v159 offset:41984
	ds_read_b64_tr_b16 v[232:233], v159 offset:42496
	v_exp_f32_e32 v248, v248
	v_exp_f32_e32 v249, v249
	v_add_f32_e32 v157, v157, v248
	v_add_f32_e32 v157, v157, v249
	v_cvt_pk_bf16_f32 v243, v248, v249
	s_waitcnt lgkmcnt(15)
	v_mfma_f32_32x32x16_bf16 v[50:65], v[234:237], v[74:77], v[50:65]
	ds_read_b64_tr_b16 v[234:235], v159 offset:43008
	ds_read_b64_tr_b16 v[236:237], v159 offset:43520
	v_exp_f32_e32 v250, v250
	v_exp_f32_e32 v251, v251
	v_add_f32_e32 v156, v156, v250
	v_add_f32_e32 v156, v156, v251
	v_cvt_pk_bf16_f32 v244, v250, v251
	s_waitcnt lgkmcnt(15)
	v_mfma_f32_32x32x16_bf16 v[34:49], v[164:167], v[74:77], v[34:49]
	ds_read_b64_tr_b16 v[164:165], v159 offset:44032
	ds_read_b64_tr_b16 v[166:167], v159 offset:44544
	v_exp_f32_e32 v252, v252
	v_exp_f32_e32 v253, v253
	v_add_f32_e32 v157, v157, v252
	v_add_f32_e32 v157, v157, v253
	v_cvt_pk_bf16_f32 v245, v252, v253
	s_waitcnt lgkmcnt(15)
	v_mfma_f32_32x32x16_bf16 v[50:65], v[168:171], v[70:73], v[50:65]
	v_exp_f32_e32 v180, v180
	v_exp_f32_e32 v181, v181
	v_add_f32_e32 v156, v156, v180
	v_add_f32_e32 v156, v156, v181
	v_cvt_pk_bf16_f32 v180, v180, v181
	s_waitcnt lgkmcnt(15)
	v_mfma_f32_32x32x16_bf16 v[34:49], v[172:175], v[70:73], v[34:49]
	v_exp_f32_e32 v182, v182
	v_exp_f32_e32 v183, v183
	v_add_f32_e32 v157, v157, v182
	v_add_f32_e32 v157, v157, v183
	v_cvt_pk_bf16_f32 v181, v182, v183
	s_waitcnt lgkmcnt(15)
	v_mfma_f32_32x32x16_bf16 v[50:65], v[148:151], v[66:69], v[50:65]
	v_exp_f32_e32 v184, v184
	v_exp_f32_e32 v185, v185
	v_add_f32_e32 v156, v156, v184
	v_add_f32_e32 v156, v156, v185
	v_cvt_pk_bf16_f32 v182, v184, v185
	s_waitcnt lgkmcnt(15)
	v_mfma_f32_32x32x16_bf16 v[34:49], v[152:155], v[66:69], v[34:49]
	v_exp_f32_e32 v186, v186
	v_exp_f32_e32 v187, v187
	v_add_f32_e32 v157, v157, v186
	v_add_f32_e32 v157, v157, v187
	v_cvt_pk_bf16_f32 v183, v186, v187
	s_nop 1
	s_waitcnt lgkmcnt(0)
	v_mfma_f32_32x32x16_bf16 v[18:33], v[238:241], v[196:199], v[18:33]
	v_exp_f32_e32 v188, v188
	v_exp_f32_e32 v189, v189
	v_add_f32_e32 v156, v156, v188
	v_add_f32_e32 v156, v156, v189
	v_cvt_pk_bf16_f32 v184, v188, v189
	s_nop 1
	v_mfma_f32_32x32x16_bf16 v[2:17], v[238:241], v[212:215], v[2:17]
	s_mul_i32 s63, s61, 0x3000
	s_add_i32 s4, s62, 2
	s_cmp_ge_u32 s4, s90
	s_cbranch_scc1 .Lat_u2y_nodma
	s_add_i32 s4, s63, 0xffffd000
	s_cmp_lg_u32 s61, 0
	s_cselect_b32 s4, s4, 0x6000
	s_add_i32 s5, s4, s58
	s_mov_b32 m0, s5
	s_add_i32 s4, s4, s59
	global_load_lds_dwordx4 v[126:127], off
	s_mov_b32 m0, s4
	s_lshl_b32 s5, s64, 13
	global_load_lds_dwordx4 v[122:123], off
	s_xor_b32 s5, s5, 0x4000
	s_add_i32 s5, s5, s60
	s_mov_b32 m0, s5
	s_nop 0
	global_load_lds_dwordx4 v[124:125], off
; __device__ __forceinline__ void cmask(f32x16& p0, f32x16& p1, int jb, int qrel, int hi) {
;     const float NEG = -INFINITY; const int kb = 64 * jb + 4 * hi;
; #pragma unroll
;     for (int r = 0; r < 16; ++r) { const int kv = kb + (r & 3) + 8 * (r >> 2); if (kv > qrel) p0[r] = NEG; if (kv + 32 > qrel) p1[r] = NEG; }
; }
; __device__ __forceinline__ void glds16(const void* gsrc, unsigned lds_dst) { unsigned keep;
;     asm volatile("s_mov_b32 %0, m0\n\ts_mov_b32 m0, %2\n\ts_nop 0\n\tglobal_load_lds_dwordx4 %1, off\n\ts_mov_b32 m0, %0" : "=&s"(keep) : "v"(gsrc), "s"(lds_dst) : "memory"); }
; __device__ __forceinline__ float max3f(float a, float b, float c) { return __builtin_fmaxf(__builtin_fmaxf(a, b), c); }
; __device__ __forceinline__ float rowmax(const f32x16& p0, const f32x16& p1) {
;     float a = max3f(p0[0], p0[1], p1[0]), b = max3f(p0[2], p0[3], p1[1]); a = max3f(a, p1[2], p1[3]);
; #pragma unroll
;     for (int r = 4; r < 16; r += 4) { a = max3f(a, p0[r], p0[r + 1]); b = max3f(b, p0[r + 2], p0[r + 3]); a = max3f(a, p1[r], p1[r + 1]); b = max3f(b, p1[r + 2], p1[r + 3]); }
;     const float m = __builtin_fmaxf(a, b);
;     auto rr = __builtin_amdgcn_permlane32_swap(__float_as_uint(m), __float_as_uint(m), false, false);
;     return __builtin_fmaxf(__uint_as_float(rr[0]), __uint_as_float(rr[1]));
; }
.Lat_u2y_nodma:
	v_lshl_add_u64 v[126:127], v[126:127], 0, s[34:35]
	v_lshl_add_u64 v[122:123], v[122:123], 0, s[20:21]
	v_lshl_add_u64 v[124:125], v[124:125], 0, s[34:35]
	v_exp_f32_e32 v190, v190
	v_exp_f32_e32 v191, v191
	v_add_f32_e32 v157, v157, v190
	v_add_f32_e32 v157, v157, v191
	v_cvt_pk_bf16_f32 v185, v190, v191
	s_nop 1
	v_mfma_f32_32x32x16_bf16 v[18:33], v[242:245], v[200:203], v[18:33]
	v_exp_f32_e32 v192, v192
	v_exp_f32_e32 v193, v193
	v_add_f32_e32 v156, v156, v192
	v_add_f32_e32 v156, v156, v193
	v_cvt_pk_bf16_f32 v186, v192, v193
	s_nop 1
	v_mfma_f32_32x32x16_bf16 v[2:17], v[242:245], v[230:233], v[2:17]
	v_exp_f32_e32 v194, v194
	v_exp_f32_e32 v195, v195
	v_add_f32_e32 v157, v157, v194
	v_add_f32_e32 v157, v157, v195
	v_cvt_pk_bf16_f32 v187, v194, v195
	s_nop 1
	v_mfma_f32_32x32x16_bf16 v[18:33], v[180:183], v[204:207], v[18:33]
	v_mfma_f32_32x32x16_bf16 v[2:17], v[180:183], v[234:237], v[2:17]
	v_mfma_f32_32x32x16_bf16 v[18:33], v[184:187], v[208:211], v[18:33]
	v_mfma_f32_32x32x16_bf16 v[2:17], v[184:187], v[164:167], v[2:17]
	v_add_f32_e32 v156, v156, v157
	v_add_f32_e32 v128, v128, v156
	s_cmp_lt_u32 s62, s91
	s_cbranch_scc1 .Lat_u2y_nomask
	s_sub_i32 s4, s62, s91
	s_lshl_b32 s4, s4, 6
	s_nop 7
	s_nop 7
	v_lshl_add_u32 v133, v142, 2, s4
	v_sub_u32_e32 v133, v145, v133
	v_cmp_gt_i32_e32 vcc, 0, v133
	s_nop 1
	v_cndmask_b32_e32 v50, v50, v220, vcc
	v_cmp_gt_i32_e32 vcc, 1, v133
	s_nop 1
	v_cndmask_b32_e32 v51, v51, v220, vcc
	v_cmp_gt_i32_e32 vcc, 2, v133
	s_nop 1
	v_cndmask_b32_e32 v52, v52, v220, vcc
	v_cmp_gt_i32_e32 vcc, 3, v133
	s_nop 1
	v_cndmask_b32_e32 v53, v53, v220, vcc
	v_cmp_gt_i32_e32 vcc, 8, v133
	s_nop 1
	v_cndmask_b32_e32 v54, v54, v220, vcc
	v_cmp_gt_i32_e32 vcc, 9, v133
	s_nop 1
	v_cndmask_b32_e32 v55, v55, v220, vcc
	v_cmp_gt_i32_e32 vcc, 10, v133
	s_nop 1
	v_cndmask_b32_e32 v56, v56, v220, vcc
	v_cmp_gt_i32_e32 vcc, 11, v133
	s_nop 1
	v_cndmask_b32_e32 v57, v57, v220, vcc
	v_cmp_gt_i32_e32 vcc, 16, v133
	s_nop 1
	v_cndmask_b32_e32 v58, v58, v220, vcc
	v_cmp_gt_i32_e32 vcc, 17, v133
	s_nop 1
	v_cndmask_b32_e32 v59, v59, v220, vcc
	v_cmp_gt_i32_e32 vcc, 18, v133
	s_nop 1
	v_cndmask_b32_e32 v60, v60, v220, vcc
	v_cmp_gt_i32_e32 vcc, 19, v133
	s_nop 1
	v_cndmask_b32_e32 v61, v61, v220, vcc
	v_cmp_gt_i32_e32 vcc, 24, v133
	s_nop 1
	v_cndmask_b32_e32 v62, v62, v220, vcc
	v_cmp_gt_i32_e32 vcc, 25, v133
	s_nop 1
	v_cndmask_b32_e32 v63, v63, v220, vcc
	v_cmp_gt_i32_e32 vcc, 26, v133
	s_nop 1
	v_cndmask_b32_e32 v64, v64, v220, vcc
	v_cmp_gt_i32_e32 vcc, 27, v133
	s_nop 1
	v_cndmask_b32_e32 v65, v65, v220, vcc
	v_cmp_gt_i32_e32 vcc, 32, v133
	s_nop 1
	v_cndmask_b32_e32 v34, v34, v220, vcc
	v_cmp_gt_i32_e32 vcc, 33, v133
	s_nop 1
	v_cndmask_b32_e32 v35, v35, v220, vcc
	v_cmp_gt_i32_e32 vcc, 34, v133
	s_nop 1
	v_cndmask_b32_e32 v36, v36, v220, vcc
	v_cmp_gt_i32_e32 vcc, 35, v133
	s_nop 1
	v_cndmask_b32_e32 v37, v37, v220, vcc
	v_cmp_gt_i32_e32 vcc, 40, v133
	s_nop 1
	v_cndmask_b32_e32 v38, v38, v220, vcc
	v_cmp_gt_i32_e32 vcc, 41, v133
	s_nop 1
	v_cndmask_b32_e32 v39, v39, v220, vcc
	v_cmp_gt_i32_e32 vcc, 42, v133
	s_nop 1
	v_cndmask_b32_e32 v40, v40, v220, vcc
	v_cmp_gt_i32_e32 vcc, 43, v133
	s_nop 1
	v_cndmask_b32_e32 v41, v41, v220, vcc
	v_cmp_gt_i32_e32 vcc, 48, v133
	s_nop 1
	v_cndmask_b32_e32 v42, v42, v220, vcc
	v_cmp_gt_i32_e32 vcc, 49, v133
	s_nop 1
	v_cndmask_b32_e32 v43, v43, v220, vcc
	v_cmp_gt_i32_e32 vcc, 50, v133
	s_nop 1
	v_cndmask_b32_e32 v44, v44, v220, vcc
	v_cmp_gt_i32_e32 vcc, 51, v133
	s_nop 1
	v_cndmask_b32_e32 v45, v45, v220, vcc
	v_cmp_gt_i32_e32 vcc, 56, v133
	s_nop 1
	v_cndmask_b32_e32 v46, v46, v220, vcc
	v_cmp_gt_i32_e32 vcc, 57, v133
	s_nop 1
	v_cndmask_b32_e32 v47, v47, v220, vcc
	v_cmp_gt_i32_e32 vcc, 58, v133
	s_nop 1
	v_cndmask_b32_e32 v48, v48, v220, vcc
	v_cmp_gt_i32_e32 vcc, 59, v133
	s_nop 1
	v_cndmask_b32_e32 v49, v49, v220, vcc
.Lat_u2y_nomask:
	v_max3_f32 v131, v50, v51, v52
	v_max3_f32 v132, v53, v54, v55
	v_max3_f32 v131, v131, v56, v57
	v_max3_f32 v132, v132, v58, v59
	v_max3_f32 v131, v131, v60, v61
	v_max3_f32 v132, v132, v62, v63
	v_max3_f32 v131, v131, v64, v65
	v_max3_f32 v132, v132, v34, v35
	v_max3_f32 v131, v131, v36, v37
	v_max3_f32 v132, v132, v38, v39
	v_max3_f32 v131, v131, v40, v41
	v_max3_f32 v132, v132, v42, v43
	v_max3_f32 v131, v131, v44, v45
	v_max3_f32 v132, v132, v46, v47
	v_max3_f32 v131, v131, v48, v49
	v_max_f32_e32 v131, v131, v132
	v_cmp_lt_f32_e32 vcc, 0x41000000, v131
	s_cbranch_vccnz .Lat_u2y_rare
.Lat_u2y_back:
	s_add_i32 s62, s62, 1
	s_add_i32 s4, s61, 1
	s_cmp_lg_u32 s61, 2
	s_cselect_b32 s61, s4, 0
	s_add_i32 s64, s64, 1
	s_and_b32 s64, s64, 3
.Lat_u2y_end:
	s_branch .Lat_u2_loop
; #define V_LOAD(vs) do { const LAS char* vp_ = vp0 + (vs) * VSLOT; \
;         _Pragma("unroll") for (int i_ = 0; i_ < 8; ++i_) { vlo[i_] = vtr(vp_ + ((i_ >> 2) * 4096 + (i_ & 3) * 1024)); vhi[i_] = vtr(vp_ + ((i_ >> 2) * 4096 + (i_ & 3) * 1024 + 512)); } SBAR(); } while (0)
; __device__ __forceinline__ void attn_unit(int b, int h, int qb, const bf16* Q, const bf16* __restrict__ Kn, const bf16* __restrict__ Kpe, const bf16* __restrict__ V, bf16* O, float* ASS, LAS char* shm) {
;     ...
;         V_LOAD((vs + 3) & 3);
;         SOFTMAX();
;         PV_MMA();
.Lat_u2_tail:
	s_waitcnt lgkmcnt(0)
	s_lshr_b32 s4, s56, 1
	s_sub_u32 s4, s62, s4
	s_sub_u32 s4, s4, 1
	s_cmp_gt_i32 s4, s91
	s_cbranch_scc1 .Lat_u2t_skip
	s_lshl_b32 s4, s64, 13
	s_add_i32 s4, s4, 0x6000
	s_and_b32 s4, s4, 0x6000
	v_add_u32_e32 v159, s4, v143
	ds_read_b64_tr_b16 v[196:197], v159 offset:36864
	ds_read_b64_tr_b16 v[198:199], v159 offset:37376
	ds_read_b64_tr_b16 v[200:201], v159 offset:37888
	ds_read_b64_tr_b16 v[202:203], v159 offset:38400
	ds_read_b64_tr_b16 v[204:205], v159 offset:38912
	ds_read_b64_tr_b16 v[206:207], v159 offset:39424
	ds_read_b64_tr_b16 v[208:209], v159 offset:39936
	ds_read_b64_tr_b16 v[210:211], v159 offset:40448
	ds_read_b64_tr_b16 v[212:213], v159 offset:40960
	ds_read_b64_tr_b16 v[214:215], v159 offset:41472
	ds_read_b64_tr_b16 v[230:231], v159 offset:41984
	ds_read_b64_tr_b16 v[232:233], v159 offset:42496
	ds_read_b64_tr_b16 v[234:235], v159 offset:43008
	ds_read_b64_tr_b16 v[236:237], v159 offset:43520
	ds_read_b64_tr_b16 v[164:165], v159 offset:44032
	ds_read_b64_tr_b16 v[166:167], v159 offset:44544
	v_mov_b32_e32 v156, 0
	v_mov_b32_e32 v157, 0
	v_exp_f32_e32 v238, v238
	v_exp_f32_e32 v239, v239
	v_add_f32_e32 v156, v156, v238
	v_add_f32_e32 v156, v156, v239
	v_cvt_pk_bf16_f32 v238, v238, v239
	v_exp_f32_e32 v240, v240
	v_exp_f32_e32 v241, v241
	v_add_f32_e32 v157, v157, v240
	v_add_f32_e32 v157, v157, v241
	v_cvt_pk_bf16_f32 v239, v240, v241
	v_exp_f32_e32 v242, v242
	v_exp_f32_e32 v243, v243
	v_add_f32_e32 v156, v156, v242
	v_add_f32_e32 v156, v156, v243
	v_cvt_pk_bf16_f32 v240, v242, v243
	v_exp_f32_e32 v244, v244
	v_exp_f32_e32 v245, v245
	v_add_f32_e32 v157, v157, v244
	v_add_f32_e32 v157, v157, v245
	v_cvt_pk_bf16_f32 v241, v244, v245
	v_exp_f32_e32 v246, v246
	v_exp_f32_e32 v247, v247
	v_add_f32_e32 v156, v156, v246
	v_add_f32_e32 v156, v156, v247
	v_cvt_pk_bf16_f32 v242, v246, v247
	v_exp_f32_e32 v248, v248
	v_exp_f32_e32 v249, v249
	v_add_f32_e32 v157, v157, v248
	v_add_f32_e32 v157, v157, v249
	v_cvt_pk_bf16_f32 v243, v248, v249
	v_exp_f32_e32 v250, v250
	v_exp_f32_e32 v251, v251
	v_add_f32_e32 v156, v156, v250
	v_add_f32_e32 v156, v156, v251
	v_cvt_pk_bf16_f32 v244, v250, v251
	v_exp_f32_e32 v252, v252
	v_exp_f32_e32 v253, v253
	v_add_f32_e32 v157, v157, v252
	v_add_f32_e32 v157, v157, v253
	v_cvt_pk_bf16_f32 v245, v252, v253
	v_exp_f32_e32 v180, v180
	v_exp_f32_e32 v181, v181
	v_add_f32_e32 v156, v156, v180
	v_add_f32_e32 v156, v156, v181
	v_cvt_pk_bf16_f32 v180, v180, v181
	v_exp_f32_e32 v182, v182
	v_exp_f32_e32 v183, v183
	v_add_f32_e32 v157, v157, v182
	v_add_f32_e32 v157, v157, v183
	v_cvt_pk_bf16_f32 v181, v182, v183
	v_exp_f32_e32 v184, v184
	v_exp_f32_e32 v185, v185
	v_add_f32_e32 v156, v156, v184
	v_add_f32_e32 v156, v156, v185
	v_cvt_pk_bf16_f32 v182, v184, v185
	v_exp_f32_e32 v186, v186
	v_exp_f32_e32 v187, v187
	v_add_f32_e32 v157, v157, v186
	v_add_f32_e32 v157, v157, v187
	v_cvt_pk_bf16_f32 v183, v186, v187
	v_exp_f32_e32 v188, v188
	v_exp_f32_e32 v189, v189
	v_add_f32_e32 v156, v156, v188
	v_add_f32_e32 v156, v156, v189
	v_cvt_pk_bf16_f32 v184, v188, v189
	v_exp_f32_e32 v190, v190
	v_exp_f32_e32 v191, v191
	v_add_f32_e32 v157, v157, v190
	v_add_f32_e32 v157, v157, v191
	v_cvt_pk_bf16_f32 v185, v190, v191
	v_exp_f32_e32 v192, v192
	v_exp_f32_e32 v193, v193
	v_add_f32_e32 v156, v156, v192
	v_add_f32_e32 v156, v156, v193
	v_cvt_pk_bf16_f32 v186, v192, v193
	v_exp_f32_e32 v194, v194
	v_exp_f32_e32 v195, v195
	v_add_f32_e32 v157, v157, v194
	v_add_f32_e32 v157, v157, v195
	v_cvt_pk_bf16_f32 v187, v194, v195
	v_add_f32_e32 v156, v156, v157
	v_add_f32_e32 v128, v128, v156
	s_waitcnt lgkmcnt(0)
	v_mfma_f32_32x32x16_bf16 v[18:33], v[238:241], v[196:199], v[18:33]
	v_mfma_f32_32x32x16_bf16 v[2:17], v[238:241], v[212:215], v[2:17]
	v_mfma_f32_32x32x16_bf16 v[18:33], v[242:245], v[200:203], v[18:33]
	v_mfma_f32_32x32x16_bf16 v[2:17], v[242:245], v[230:233], v[2:17]
	v_mfma_f32_32x32x16_bf16 v[18:33], v[180:183], v[204:207], v[18:33]
	v_mfma_f32_32x32x16_bf16 v[2:17], v[180:183], v[234:237], v[2:17]
	v_mfma_f32_32x32x16_bf16 v[18:33], v[184:187], v[208:211], v[18:33]
	v_mfma_f32_32x32x16_bf16 v[2:17], v[184:187], v[164:167], v[2:17]
.Lat_u2t_skip:
	s_mov_b32 m0, s65
	v_mov_b32_e32 v122, v128
	s_mov_b64 s[38:39], 0
	s_branch .LBB0_936
; __device__ __forceinline__ float rowmax(const f32x16& p0, const f32x16& p1) {
;     ...
;     auto rr = __builtin_amdgcn_permlane32_swap(__float_as_uint(m), __float_as_uint(m), false, false);
;     return __builtin_fmaxf(__uint_as_float(rr[0]), __uint_as_float(rr[1]));
.Lat_u2x_rare:
	s_nop 15
	v_mov_b32_e32 v132, v131
	s_nop 1
	v_permlane32_swap_b32_e32 v131, v132
	s_nop 0
	v_max_f32_e32 v131, v131, v132
	v_max_f32_e32 v132, 0, v131
	v_exp_f32_e64 v133, -v132
	v_add_f32_e32 v130, v130, v132
	s_nop 0
	s_and_saveexec_b64 s[54:55], s[38:39]
	ds_write_b32 v147, v133
	s_or_b64 exec, exec, s[54:55]
	v_mul_f32_e32 v128, v128, v133
	v_sub_f32_e32 v104, v104, v132
	v_sub_f32_e32 v105, v105, v132
	v_sub_f32_e32 v106, v106, v132
	v_sub_f32_e32 v107, v107, v132
	v_sub_f32_e32 v108, v108, v132
	v_sub_f32_e32 v109, v109, v132
	v_sub_f32_e32 v110, v110, v132
	v_sub_f32_e32 v111, v111, v132
	v_sub_f32_e32 v112, v112, v132
	v_sub_f32_e32 v113, v113, v132
	v_sub_f32_e32 v114, v114, v132
	v_sub_f32_e32 v115, v115, v132
	v_sub_f32_e32 v116, v116, v132
	v_sub_f32_e32 v117, v117, v132
	v_sub_f32_e32 v118, v118, v132
	v_sub_f32_e32 v119, v119, v132
	v_sub_f32_e32 v238, v238, v132
	v_sub_f32_e32 v239, v239, v132
	v_sub_f32_e32 v240, v240, v132
	v_sub_f32_e32 v241, v241, v132
	v_sub_f32_e32 v242, v242, v132
	v_sub_f32_e32 v243, v243, v132
	v_sub_f32_e32 v244, v244, v132
	v_sub_f32_e32 v245, v245, v132
	v_sub_f32_e32 v246, v246, v132
	v_sub_f32_e32 v247, v247, v132
	v_sub_f32_e32 v248, v248, v132
	v_sub_f32_e32 v249, v249, v132
	v_sub_f32_e32 v250, v250, v132
	v_sub_f32_e32 v251, v251, v132
	v_sub_f32_e32 v252, v252, v132
	v_sub_f32_e32 v253, v253, v132
	v_sub_f32_e32 v180, v180, v132
	v_sub_f32_e32 v181, v181, v132
	v_sub_f32_e32 v182, v182, v132
	v_sub_f32_e32 v183, v183, v132
	v_sub_f32_e32 v184, v184, v132
	v_sub_f32_e32 v185, v185, v132
	v_sub_f32_e32 v186, v186, v132
	v_sub_f32_e32 v187, v187, v132
	v_sub_f32_e32 v188, v188, v132
	v_sub_f32_e32 v189, v189, v132
	v_sub_f32_e32 v190, v190, v132
	v_sub_f32_e32 v191, v191, v132
	v_sub_f32_e32 v192, v192, v132
	v_sub_f32_e32 v193, v193, v132
	v_sub_f32_e32 v194, v194, v132
	v_sub_f32_e32 v195, v195, v132
	s_waitcnt lgkmcnt(0)
	v_add_u32_e32 v133, s57, v129
	ds_read_b128 v[90:93], v133
	ds_read_b128 v[94:97], v133 offset:32
	ds_read_b128 v[98:101], v133 offset:64
	ds_read_b128 v[176:179], v133 offset:96
	s_waitcnt lgkmcnt(0)
	v_mul_f32_e32 v18, v18, v90
	v_mul_f32_e32 v2, v2, v90
	v_mul_f32_e32 v19, v19, v91
	v_mul_f32_e32 v3, v3, v91
	v_mul_f32_e32 v20, v20, v92
	v_mul_f32_e32 v4, v4, v92
	v_mul_f32_e32 v21, v21, v93
	v_mul_f32_e32 v5, v5, v93
	v_mul_f32_e32 v22, v22, v94
	v_mul_f32_e32 v6, v6, v94
	v_mul_f32_e32 v23, v23, v95
	v_mul_f32_e32 v7, v7, v95
	v_mul_f32_e32 v24, v24, v96
	v_mul_f32_e32 v8, v8, v96
	v_mul_f32_e32 v25, v25, v97
	v_mul_f32_e32 v9, v9, v97
	v_mul_f32_e32 v26, v26, v98
	v_mul_f32_e32 v10, v10, v98
	v_mul_f32_e32 v27, v27, v99
	v_mul_f32_e32 v11, v11, v99
	v_mul_f32_e32 v28, v28, v100
	v_mul_f32_e32 v12, v12, v100
	v_mul_f32_e32 v29, v29, v101
	v_mul_f32_e32 v13, v13, v101
	v_mul_f32_e32 v30, v30, v176
	v_mul_f32_e32 v14, v14, v176
	v_mul_f32_e32 v31, v31, v177
	v_mul_f32_e32 v15, v15, v177
	v_mul_f32_e32 v32, v32, v178
	v_mul_f32_e32 v16, v16, v178
	v_mul_f32_e32 v33, v33, v179
	v_mul_f32_e32 v17, v17, v179
	s_branch .Lat_u2x_back
.Lat_u2y_rare:
	s_nop 15
	v_mov_b32_e32 v132, v131
	s_nop 1
	v_permlane32_swap_b32_e32 v131, v132
	s_nop 0
	v_max_f32_e32 v131, v131, v132
	v_max_f32_e32 v132, 0, v131
	v_exp_f32_e64 v133, -v132
	v_add_f32_e32 v130, v130, v132
	s_nop 0
	s_and_saveexec_b64 s[54:55], s[38:39]
	ds_write_b32 v147, v133
	s_or_b64 exec, exec, s[54:55]
	v_mul_f32_e32 v128, v128, v133
	v_sub_f32_e32 v104, v104, v132
	v_sub_f32_e32 v105, v105, v132
	v_sub_f32_e32 v106, v106, v132
	v_sub_f32_e32 v107, v107, v132
	v_sub_f32_e32 v108, v108, v132
	v_sub_f32_e32 v109, v109, v132
	v_sub_f32_e32 v110, v110, v132
	v_sub_f32_e32 v111, v111, v132
	v_sub_f32_e32 v112, v112, v132
	v_sub_f32_e32 v113, v113, v132
	v_sub_f32_e32 v114, v114, v132
	v_sub_f32_e32 v115, v115, v132
	v_sub_f32_e32 v116, v116, v132
	v_sub_f32_e32 v117, v117, v132
	v_sub_f32_e32 v118, v118, v132
	v_sub_f32_e32 v119, v119, v132
	v_sub_f32_e32 v50, v50, v132
	v_sub_f32_e32 v51, v51, v132
	v_sub_f32_e32 v52, v52, v132
	v_sub_f32_e32 v53, v53, v132
	v_sub_f32_e32 v54, v54, v132
	v_sub_f32_e32 v55, v55, v132
	v_sub_f32_e32 v56, v56, v132
	v_sub_f32_e32 v57, v57, v132
	v_sub_f32_e32 v58, v58, v132
	v_sub_f32_e32 v59, v59, v132
	v_sub_f32_e32 v60, v60, v132
	v_sub_f32_e32 v61, v61, v132
	v_sub_f32_e32 v62, v62, v132
	v_sub_f32_e32 v63, v63, v132
	v_sub_f32_e32 v64, v64, v132
	v_sub_f32_e32 v65, v65, v132
	v_sub_f32_e32 v34, v34, v132
	v_sub_f32_e32 v35, v35, v132
	v_sub_f32_e32 v36, v36, v132
	v_sub_f32_e32 v37, v37, v132
	v_sub_f32_e32 v38, v38, v132
	v_sub_f32_e32 v39, v39, v132
	v_sub_f32_e32 v40, v40, v132
	v_sub_f32_e32 v41, v41, v132
	v_sub_f32_e32 v42, v42, v132
	v_sub_f32_e32 v43, v43, v132
	v_sub_f32_e32 v44, v44, v132
	v_sub_f32_e32 v45, v45, v132
	v_sub_f32_e32 v46, v46, v132
	v_sub_f32_e32 v47, v47, v132
	v_sub_f32_e32 v48, v48, v132
	v_sub_f32_e32 v49, v49, v132
	s_waitcnt lgkmcnt(0)
	v_add_u32_e32 v133, s57, v129
	ds_read_b128 v[90:93], v133
	ds_read_b128 v[94:97], v133 offset:32
	ds_read_b128 v[98:101], v133 offset:64
	ds_read_b128 v[176:179], v133 offset:96
	s_waitcnt lgkmcnt(0)
	v_mul_f32_e32 v18, v18, v90
	v_mul_f32_e32 v2, v2, v90
	v_mul_f32_e32 v19, v19, v91
	v_mul_f32_e32 v3, v3, v91
	v_mul_f32_e32 v20, v20, v92
	v_mul_f32_e32 v4, v4, v92
	v_mul_f32_e32 v21, v21, v93
	v_mul_f32_e32 v5, v5, v93
	v_mul_f32_e32 v22, v22, v94
	v_mul_f32_e32 v6, v6, v94
	v_mul_f32_e32 v23, v23, v95
	v_mul_f32_e32 v7, v7, v95
	v_mul_f32_e32 v24, v24, v96
	v_mul_f32_e32 v8, v8, v96
	v_mul_f32_e32 v25, v25, v97
	v_mul_f32_e32 v9, v9, v97
	v_mul_f32_e32 v26, v26, v98
	v_mul_f32_e32 v10, v10, v98
	v_mul_f32_e32 v27, v27, v99
	v_mul_f32_e32 v11, v11, v99
	v_mul_f32_e32 v28, v28, v100
	v_mul_f32_e32 v12, v12, v100
	v_mul_f32_e32 v29, v29, v101
	v_mul_f32_e32 v13, v13, v101
	v_mul_f32_e32 v30, v30, v176
	v_mul_f32_e32 v14, v14, v176
	v_mul_f32_e32 v31, v31, v177
	v_mul_f32_e32 v15, v15, v177
	v_mul_f32_e32 v32, v32, v178
	v_mul_f32_e32 v16, v16, v178
	v_mul_f32_e32 v33, v33, v179
	v_mul_f32_e32 v17, v17, v179
	s_branch .Lat_u2y_back
.Lat_u2x_noqk:
	s_lshr_b32 s4, s56, 1
	s_sub_u32 s4, s62, s4
	s_sub_u32 s4, s4, 1
	s_cmp_gt_i32 s4, s91
	s_cbranch_scc1 .Lat_u2x_idle
	s_lshl_b32 s4, s64, 13
	s_add_i32 s4, s4, 0x6000
	s_and_b32 s4, s4, 0x6000
	v_add_u32_e32 v159, s4, v143
	ds_read_b64_tr_b16 v[196:197], v159 offset:36864
	ds_read_b64_tr_b16 v[198:199], v159 offset:37376
	ds_read_b64_tr_b16 v[200:201], v159 offset:37888
	ds_read_b64_tr_b16 v[202:203], v159 offset:38400
	ds_read_b64_tr_b16 v[204:205], v159 offset:38912
	ds_read_b64_tr_b16 v[206:207], v159 offset:39424
	ds_read_b64_tr_b16 v[208:209], v159 offset:39936
	ds_read_b64_tr_b16 v[210:211], v159 offset:40448
	ds_read_b64_tr_b16 v[212:213], v159 offset:40960
	ds_read_b64_tr_b16 v[214:215], v159 offset:41472
	ds_read_b64_tr_b16 v[230:231], v159 offset:41984
	ds_read_b64_tr_b16 v[232:233], v159 offset:42496
	ds_read_b64_tr_b16 v[234:235], v159 offset:43008
	ds_read_b64_tr_b16 v[236:237], v159 offset:43520
	ds_read_b64_tr_b16 v[164:165], v159 offset:44032
	ds_read_b64_tr_b16 v[166:167], v159 offset:44544
	v_mov_b32_e32 v156, 0
	v_mov_b32_e32 v157, 0
	v_exp_f32_e32 v50, v50
	v_exp_f32_e32 v51, v51
	v_add_f32_e32 v156, v156, v50
	v_add_f32_e32 v156, v156, v51
	v_cvt_pk_bf16_f32 v50, v50, v51
	v_exp_f32_e32 v52, v52
	v_exp_f32_e32 v53, v53
	v_add_f32_e32 v157, v157, v52
	v_add_f32_e32 v157, v157, v53
	v_cvt_pk_bf16_f32 v51, v52, v53
	v_exp_f32_e32 v54, v54
	v_exp_f32_e32 v55, v55
	v_add_f32_e32 v156, v156, v54
	v_add_f32_e32 v156, v156, v55
	v_cvt_pk_bf16_f32 v52, v54, v55
	v_exp_f32_e32 v56, v56
	v_exp_f32_e32 v57, v57
	v_add_f32_e32 v157, v157, v56
	v_add_f32_e32 v157, v157, v57
	v_cvt_pk_bf16_f32 v53, v56, v57
	v_exp_f32_e32 v58, v58
	v_exp_f32_e32 v59, v59
	v_add_f32_e32 v156, v156, v58
	v_add_f32_e32 v156, v156, v59
	v_cvt_pk_bf16_f32 v54, v58, v59
	v_exp_f32_e32 v60, v60
	v_exp_f32_e32 v61, v61
	v_add_f32_e32 v157, v157, v60
	v_add_f32_e32 v157, v157, v61
	v_cvt_pk_bf16_f32 v55, v60, v61
	v_exp_f32_e32 v62, v62
	v_exp_f32_e32 v63, v63
	v_add_f32_e32 v156, v156, v62
	v_add_f32_e32 v156, v156, v63
	v_cvt_pk_bf16_f32 v56, v62, v63
	v_exp_f32_e32 v64, v64
	v_exp_f32_e32 v65, v65
	v_add_f32_e32 v157, v157, v64
	v_add_f32_e32 v157, v157, v65
	v_cvt_pk_bf16_f32 v57, v64, v65
	s_nop 1
	s_waitcnt lgkmcnt(0)
	v_mfma_f32_32x32x16_bf16 v[18:33], v[50:53], v[196:199], v[18:33]
	v_exp_f32_e32 v34, v34
	v_exp_f32_e32 v35, v35
	v_add_f32_e32 v156, v156, v34
	v_add_f32_e32 v156, v156, v35
	v_cvt_pk_bf16_f32 v34, v34, v35
	v_exp_f32_e32 v36, v36
	v_exp_f32_e32 v37, v37
	v_add_f32_e32 v157, v157, v36
	v_add_f32_e32 v157, v157, v37
	v_cvt_pk_bf16_f32 v35, v36, v37
	v_mfma_f32_32x32x16_bf16 v[2:17], v[50:53], v[212:215], v[2:17]
	v_exp_f32_e32 v38, v38
	v_exp_f32_e32 v39, v39
	v_add_f32_e32 v156, v156, v38
	v_add_f32_e32 v156, v156, v39
	v_cvt_pk_bf16_f32 v36, v38, v39
	v_exp_f32_e32 v40, v40
	v_exp_f32_e32 v41, v41
	v_add_f32_e32 v157, v157, v40
	v_add_f32_e32 v157, v157, v41
	v_cvt_pk_bf16_f32 v37, v40, v41
	v_mfma_f32_32x32x16_bf16 v[18:33], v[54:57], v[200:203], v[18:33]
	v_exp_f32_e32 v42, v42
	v_exp_f32_e32 v43, v43
	v_add_f32_e32 v156, v156, v42
	v_add_f32_e32 v156, v156, v43
	v_cvt_pk_bf16_f32 v38, v42, v43
	v_exp_f32_e32 v44, v44
	v_exp_f32_e32 v45, v45
	v_add_f32_e32 v157, v157, v44
	v_add_f32_e32 v157, v157, v45
	v_cvt_pk_bf16_f32 v39, v44, v45
	v_mfma_f32_32x32x16_bf16 v[2:17], v[54:57], v[230:233], v[2:17]
	v_exp_f32_e32 v46, v46
	v_exp_f32_e32 v47, v47
	v_add_f32_e32 v156, v156, v46
	v_add_f32_e32 v156, v156, v47
	v_cvt_pk_bf16_f32 v40, v46, v47
	v_exp_f32_e32 v48, v48
	v_exp_f32_e32 v49, v49
	v_add_f32_e32 v157, v157, v48
	v_add_f32_e32 v157, v157, v49
	v_cvt_pk_bf16_f32 v41, v48, v49
	s_nop 1
	v_mfma_f32_32x32x16_bf16 v[18:33], v[34:37], v[204:207], v[18:33]
	v_mfma_f32_32x32x16_bf16 v[2:17], v[34:37], v[234:237], v[2:17]
	v_mfma_f32_32x32x16_bf16 v[18:33], v[38:41], v[208:211], v[18:33]
	v_mfma_f32_32x32x16_bf16 v[2:17], v[38:41], v[164:167], v[2:17]
	v_add_f32_e32 v156, v156, v157
	v_add_f32_e32 v128, v128, v156
.Lat_u2x_idle:
	s_mul_i32 s63, s61, 0x3000
	s_add_i32 s4, s62, 2
	s_cmp_ge_u32 s4, s90
	s_cbranch_scc1 .Lat_u2xn_nodma
	s_add_i32 s4, s63, 0xffffd000
	s_cmp_lg_u32 s61, 0
	s_cselect_b32 s4, s4, 0x6000
	s_add_i32 s5, s4, s58
	s_mov_b32 m0, s5
	s_add_i32 s4, s4, s59
	global_load_lds_dwordx4 v[126:127], off
	s_mov_b32 m0, s4
	s_lshl_b32 s5, s64, 13
	global_load_lds_dwordx4 v[122:123], off
	s_xor_b32 s5, s5, 0x4000
	s_add_i32 s5, s5, s60
	s_mov_b32 m0, s5
	s_nop 0
	global_load_lds_dwordx4 v[124:125], off
; __device__ __forceinline__ void attn_unit(int b, int h, int qb, const bf16* Q, const bf16* __restrict__ Kn, const bf16* __restrict__ Kpe, const bf16* __restrict__ V, bf16* O, float* ASS, LAS char* shm) {
;     ...
;             ks = (ks == 2) ? 0 : ks + 1; vs = (vs + 1) & 3;
.Lat_u2xn_nodma:
	v_lshl_add_u64 v[126:127], v[126:127], 0, s[34:35]
	v_lshl_add_u64 v[122:123], v[122:123], 0, s[20:21]
	v_lshl_add_u64 v[124:125], v[124:125], 0, s[34:35]
	s_add_i32 s62, s62, 1
	s_add_i32 s4, s61, 1
	s_cmp_lg_u32 s61, 2
	s_cselect_b32 s61, s4, 0
	s_add_i32 s64, s64, 1
	s_and_b32 s64, s64, 3
	s_branch .Lat_u2x_end
.Lat_u2y_noqk:
	s_lshr_b32 s4, s56, 1
	s_sub_u32 s4, s62, s4
	s_sub_u32 s4, s4, 1
	s_cmp_gt_i32 s4, s91
	s_cbranch_scc1 .Lat_u2y_idle
	s_lshl_b32 s4, s64, 13
	s_add_i32 s4, s4, 0x6000
	s_and_b32 s4, s4, 0x6000
	v_add_u32_e32 v159, s4, v143
	ds_read_b64_tr_b16 v[196:197], v159 offset:36864
	ds_read_b64_tr_b16 v[198:199], v159 offset:37376
	ds_read_b64_tr_b16 v[200:201], v159 offset:37888
	ds_read_b64_tr_b16 v[202:203], v159 offset:38400
	ds_read_b64_tr_b16 v[204:205], v159 offset:38912
	ds_read_b64_tr_b16 v[206:207], v159 offset:39424
	ds_read_b64_tr_b16 v[208:209], v159 offset:39936
	ds_read_b64_tr_b16 v[210:211], v159 offset:40448
	ds_read_b64_tr_b16 v[212:213], v159 offset:40960
	ds_read_b64_tr_b16 v[214:215], v159 offset:41472
	ds_read_b64_tr_b16 v[230:231], v159 offset:41984
	ds_read_b64_tr_b16 v[232:233], v159 offset:42496
	ds_read_b64_tr_b16 v[234:235], v159 offset:43008
	ds_read_b64_tr_b16 v[236:237], v159 offset:43520
	ds_read_b64_tr_b16 v[164:165], v159 offset:44032
	ds_read_b64_tr_b16 v[166:167], v159 offset:44544
	v_mov_b32_e32 v156, 0
	v_mov_b32_e32 v157, 0
	v_exp_f32_e32 v238, v238
	v_exp_f32_e32 v239, v239
	v_add_f32_e32 v156, v156, v238
	v_add_f32_e32 v156, v156, v239
	v_cvt_pk_bf16_f32 v238, v238, v239
	v_exp_f32_e32 v240, v240
	v_exp_f32_e32 v241, v241
	v_add_f32_e32 v157, v157, v240
	v_add_f32_e32 v157, v157, v241
	v_cvt_pk_bf16_f32 v239, v240, v241
	v_exp_f32_e32 v242, v242
	v_exp_f32_e32 v243, v243
	v_add_f32_e32 v156, v156, v242
	v_add_f32_e32 v156, v156, v243
	v_cvt_pk_bf16_f32 v240, v242, v243
	v_exp_f32_e32 v244, v244
	v_exp_f32_e32 v245, v245
	v_add_f32_e32 v157, v157, v244
	v_add_f32_e32 v157, v157, v245
	v_cvt_pk_bf16_f32 v241, v244, v245
	v_exp_f32_e32 v246, v246
	v_exp_f32_e32 v247, v247
	v_add_f32_e32 v156, v156, v246
	v_add_f32_e32 v156, v156, v247
	v_cvt_pk_bf16_f32 v242, v246, v247
	v_exp_f32_e32 v248, v248
	v_exp_f32_e32 v249, v249
	v_add_f32_e32 v157, v157, v248
	v_add_f32_e32 v157, v157, v249
	v_cvt_pk_bf16_f32 v243, v248, v249
	v_exp_f32_e32 v250, v250
	v_exp_f32_e32 v251, v251
	v_add_f32_e32 v156, v156, v250
	v_add_f32_e32 v156, v156, v251
	v_cvt_pk_bf16_f32 v244, v250, v251
	v_exp_f32_e32 v252, v252
	v_exp_f32_e32 v253, v253
	v_add_f32_e32 v157, v157, v252
	v_add_f32_e32 v157, v157, v253
	v_cvt_pk_bf16_f32 v245, v252, v253
	s_nop 1
	s_waitcnt lgkmcnt(0)
	v_mfma_f32_32x32x16_bf16 v[18:33], v[238:241], v[196:199], v[18:33]
	v_exp_f32_e32 v180, v180
	v_exp_f32_e32 v181, v181
	v_add_f32_e32 v156, v156, v180
	v_add_f32_e32 v156, v156, v181
	v_cvt_pk_bf16_f32 v180, v180, v181
	v_exp_f32_e32 v182, v182
	v_exp_f32_e32 v183, v183
	v_add_f32_e32 v157, v157, v182
	v_add_f32_e32 v157, v157, v183
	v_cvt_pk_bf16_f32 v181, v182, v183
	v_mfma_f32_32x32x16_bf16 v[2:17], v[238:241], v[212:215], v[2:17]
	v_exp_f32_e32 v184, v184
	v_exp_f32_e32 v185, v185
	v_add_f32_e32 v156, v156, v184
	v_add_f32_e32 v156, v156, v185
	v_cvt_pk_bf16_f32 v182, v184, v185
	v_exp_f32_e32 v186, v186
	v_exp_f32_e32 v187, v187
	v_add_f32_e32 v157, v157, v186
	v_add_f32_e32 v157, v157, v187
	v_cvt_pk_bf16_f32 v183, v186, v187
	v_mfma_f32_32x32x16_bf16 v[18:33], v[242:245], v[200:203], v[18:33]
	v_exp_f32_e32 v188, v188
	v_exp_f32_e32 v189, v189
	v_add_f32_e32 v156, v156, v188
	v_add_f32_e32 v156, v156, v189
	v_cvt_pk_bf16_f32 v184, v188, v189
	v_exp_f32_e32 v190, v190
	v_exp_f32_e32 v191, v191
	v_add_f32_e32 v157, v157, v190
	v_add_f32_e32 v157, v157, v191
	v_cvt_pk_bf16_f32 v185, v190, v191
	v_mfma_f32_32x32x16_bf16 v[2:17], v[242:245], v[230:233], v[2:17]
	v_exp_f32_e32 v192, v192
	v_exp_f32_e32 v193, v193
	v_add_f32_e32 v156, v156, v192
	v_add_f32_e32 v156, v156, v193
	v_cvt_pk_bf16_f32 v186, v192, v193
	v_exp_f32_e32 v194, v194
	v_exp_f32_e32 v195, v195
	v_add_f32_e32 v157, v157, v194
	v_add_f32_e32 v157, v157, v195
	v_cvt_pk_bf16_f32 v187, v194, v195
	s_nop 1
	v_mfma_f32_32x32x16_bf16 v[18:33], v[180:183], v[204:207], v[18:33]
	v_mfma_f32_32x32x16_bf16 v[2:17], v[180:183], v[234:237], v[2:17]
	v_mfma_f32_32x32x16_bf16 v[18:33], v[184:187], v[208:211], v[18:33]
	v_mfma_f32_32x32x16_bf16 v[2:17], v[184:187], v[164:167], v[2:17]
	v_add_f32_e32 v156, v156, v157
	v_add_f32_e32 v128, v128, v156

; __device__ __forceinline__ unsigned xb_add(unsigned* p, unsigned v) { return __hip_atomic_fetch_add(p, v, __ATOMIC_RELAXED, __HIP_MEMORY_SCOPE_AGENT); }
; __device__ __forceinline__ void xcd_local_barrier(const XcdBarrier& b, unsigned nloc) {
;     asm volatile("s_waitcnt vmcnt(0)" ::: "memory");
;     __syncthreads();
;     if (threadIdx.x == 0) {
;         unsigned* bar = b.bar;
;         __builtin_amdgcn_s_waitcnt(0);
;         const unsigned old = xb_add(&bar[XB_LSUB(b.x)], 1u);
;         const unsigned gen = old / nloc;
;         if (old + 1u == (gen + 1u) * nloc) xb_add(&bar[XB_LGEN(b.x)], 1u);
.LBB0_975:
	s_setprio 0
	v_readlane_b32 s0, v254, 60
	v_mov_b32 v0, s0
	ds_read_b32 v0, v0
	s_waitcnt lgkmcnt(0)
	s_nop 0
	v_readfirstlane_b32 s0, v0
	s_cmp_eq_u32 s0, 0
	s_cbranch_scc1 .LBB0_989
	s_waitcnt vmcnt(0)
	s_waitcnt vmcnt(0) lgkmcnt(0)
	s_barrier
	s_and_saveexec_b64 s[0:1], s[92:93]
	v_readlane_b32 s50, v255, 5
	v_readlane_b32 s51, v255, 6
	s_cbranch_execz .LBB0_995
	v_readlane_b32 s100, v255, 40
	v_readlane_b32 s4, v254, 6
	v_readlane_b32 s5, v254, 7
	s_mov_b32 s101, 0
	s_add_u32 s100, s100, 32
	s_nop 1
	v_writelane_b32 v255, s100, 40
	global_atomic_add v1, v218, s[4:5]
	buffer_inv sc1

; __device__ __forceinline__ unsigned xb_add(unsigned* p, unsigned v) { return __hip_atomic_fetch_add(p, v, __ATOMIC_RELAXED, __HIP_MEMORY_SCOPE_AGENT); }
; __device__ __forceinline__ void xcd_local_barrier(const XcdBarrier& b, unsigned nloc) {
;     asm volatile("s_waitcnt vmcnt(0)" ::: "memory");
;     __syncthreads();
;     if (threadIdx.x == 0) {
;         unsigned* bar = b.bar;
;         __builtin_amdgcn_s_waitcnt(0);
;         const unsigned old = xb_add(&bar[XB_LSUB(b.x)], 1u);
;         const unsigned gen = old / nloc;
;         if (old + 1u == (gen + 1u) * nloc) xb_add(&bar[XB_LGEN(b.x)], 1u);
.LBB0_1367:
	v_readlane_b32 s0, v254, 60
	v_mov_b32 v0, s0
	ds_read_b32 v0, v0
	s_waitcnt lgkmcnt(0)
	s_nop 0
	v_readfirstlane_b32 s0, v0
	s_cmp_eq_u32 s0, 0
	s_cbranch_scc1 .LBB0_1381
	s_waitcnt vmcnt(0)
	s_waitcnt lgkmcnt(0)
	s_barrier
	s_and_saveexec_b64 s[0:1], s[92:93]
	v_readlane_b32 s58, v255, 17
	v_readlane_b32 s6, v255, 7
	v_readlane_b32 s52, v255, 9
	v_readlane_b32 s54, v255, 11
	v_readlane_b32 s56, v255, 13
	v_readlane_b32 s59, v255, 18
	v_readlane_b32 s7, v255, 8
	v_readlane_b32 s53, v255, 10
	v_readlane_b32 s55, v255, 12
	v_readlane_b32 s57, v255, 14
	s_cbranch_execz .LBB0_1387
	v_readlane_b32 s100, v255, 40
	v_readlane_b32 s4, v254, 6
	v_readlane_b32 s5, v254, 7
	s_mov_b32 s101, 0
	s_add_u32 s100, s100, 32
	s_nop 1
	v_writelane_b32 v255, s100, 40
	global_atomic_add v1, v218, s[4:5]
	buffer_inv sc1

; __device__ __forceinline__ unsigned xb_add(unsigned* p, unsigned v) { return __hip_atomic_fetch_add(p, v, __ATOMIC_RELAXED, __HIP_MEMORY_SCOPE_AGENT); }
; __device__ __forceinline__ void xcd_local_barrier(const XcdBarrier& b, unsigned nloc) {
;     asm volatile("s_waitcnt vmcnt(0)" ::: "memory");
;     __syncthreads();
;     if (threadIdx.x == 0) {
;         unsigned* bar = b.bar;
;         __builtin_amdgcn_s_waitcnt(0);
;         const unsigned old = xb_add(&bar[XB_LSUB(b.x)], 1u);
;         const unsigned gen = old / nloc;
;         if (old + 1u == (gen + 1u) * nloc) xb_add(&bar[XB_LGEN(b.x)], 1u);
.LBB0_1467:
	v_readlane_b32 s0, v254, 60
	v_mov_b32 v0, s0
	ds_read_b32 v0, v0
	s_waitcnt lgkmcnt(0)
	s_nop 0
	v_readfirstlane_b32 s0, v0
	s_cmp_eq_u32 s0, 0
	s_cbranch_scc1 .LBB0_1481
	s_waitcnt vmcnt(0)
	s_waitcnt vmcnt(0) lgkmcnt(0)
	s_barrier
	s_and_saveexec_b64 s[0:1], s[92:93]
	s_cbranch_execz .LBB0_1487
	v_readlane_b32 s100, v255, 40
	v_readlane_b32 s4, v254, 6
	v_readlane_b32 s5, v254, 7
	s_mov_b32 s101, 0
	s_add_u32 s100, s100, 32
	s_nop 1
	v_writelane_b32 v255, s100, 40
	global_atomic_add v1, v218, s[4:5]
	buffer_inv sc1

; __device__ __forceinline__ unsigned xb_add(unsigned* p, unsigned v) { return __hip_atomic_fetch_add(p, v, __ATOMIC_RELAXED, __HIP_MEMORY_SCOPE_AGENT); }
; #define GRID_BAR() xcd_barrier(bar)
; #define SEAM_LOCAL() do { if (__builtin_amdgcn_readfirstlane((int)lds_word((unsigned)(__UINTPTR_TYPE__)lds + MISC_OFF + 68))) xcd_local_barrier(bar, 32u); else xcd_barrier(bar); } while (0)
; __device__ __forceinline__ void xcd_local_barrier(const XcdBarrier& b, unsigned nloc) {
;     asm volatile("s_waitcnt vmcnt(0)" ::: "memory");
;     __syncthreads();
;     if (threadIdx.x == 0) {
;         unsigned* bar = b.bar;
;         __builtin_amdgcn_s_waitcnt(0);
;         const unsigned old = xb_add(&bar[XB_LSUB(b.x)], 1u);
;         const unsigned gen = old / nloc;
;         if (old + 1u == (gen + 1u) * nloc) xb_add(&bar[XB_LGEN(b.x)], 1u);
; __global__ void __launch_bounds__(512, 2) trunk_fwd(Args args) {
;     ...
;         if (L + 1 < DEPTH) SEAM_LOCAL(); else GRID_BAR();
.LBB0_1587:
	v_readlane_b32 s0, v255, 19
	v_readlane_b32 s1, v255, 20
	v_readlane_b32 s78, v255, 7
	v_readlane_b32 s6, v255, 9
	v_cndmask_b32_e64 v0, 0, 1, s[0:1]
	v_readlane_b32 s52, v255, 11
	v_readlane_b32 s54, v255, 13
	v_cmp_ne_u32_e64 s[44:45], 1, v0
	s_andn2_b64 vcc, exec, s[0:1]
	s_mov_b64 s[0:1], -1
	v_readlane_b32 s79, v255, 8
	v_readlane_b32 s7, v255, 10
	v_readlane_b32 s53, v255, 12
	v_readlane_b32 s55, v255, 14
	s_cbranch_vccnz .LBB0_1663
	v_readlane_b32 s0, v254, 60
	v_mov_b32 v0, s0
	ds_read_b32 v0, v0
	s_waitcnt lgkmcnt(0)
	s_nop 0
	v_readfirstlane_b32 s0, v0
	s_cmp_eq_u32 s0, 0
	s_cbranch_scc1 .LBB0_1602
	s_waitcnt vmcnt(0)
	s_waitcnt vmcnt(0) lgkmcnt(0)
	s_barrier
	s_and_saveexec_b64 s[0:1], s[92:93]
	s_cbranch_execz .LBB0_1608
	v_readlane_b32 s100, v255, 40
	v_readlane_b32 s4, v254, 6
	v_readlane_b32 s5, v254, 7
	s_mov_b32 s101, 0
	s_add_u32 s100, s100, 32
	s_nop 1
	v_writelane_b32 v255, s100, 40
	global_atomic_add v1, v218, s[4:5]
	buffer_inv sc1
